# peeled first load segment of each unit: sleep removed and ds_reads issued before the 2 DMAs (no MFMA runs beside the leading half there)
# baseline (speedup 1.0000x reference)
.LBB0_146:
	s_ashr_i32 s25, s24, 31
	s_lshl_b64 s[26:27], s[24:25], 20
	s_add_u32 s26, s47, s26
	s_addc_u32 s27, s48, s27
	s_and_b64 s[28:29], s[38:39], exec
	s_cselect_b32 s2, s27, s41
	s_cselect_b32 s5, s26, s40
	s_ashr_i32 s23, s22, 31
	s_lshl_b64 s[28:29], s[22:23], 20
	s_add_u32 s28, s49, s28
	s_addc_u32 s29, s50, s29
	s_and_b64 s[44:45], s[38:39], exec
	s_cselect_b32 s23, s29, s43
	s_cselect_b32 s25, s28, s42
	s_add_u32 s40, s40, 0x80080
	s_addc_u32 s41, s41, 0
	s_add_u32 s31, s42, 0x100
	s_addc_u32 s62, s43, 0
	s_mov_b32 s63, -2
	s_add_u32 s42, s40, 0xfff80080
	s_addc_u32 s43, s41, -1
	s_add_i32 s71, 0, 0x10000
	s_cmp_eq_u32 s63, 28
	s_cselect_b32 s45, s2, s43
	s_cselect_b32 s44, s5, s42
	s_cselect_b32 s43, s23, s62
	s_cselect_b32 s42, s25, s31
	s_add_i32 s73, 0, 0x14000
	s_waitcnt lgkmcnt(0)
	v_add_u32_e32 v156, s71, v169
	v_add_u32_e32 v178, s73, v169
	ds_read_b128 v[132:135], v156
	ds_read_b128 v[136:139], v156 offset:1024
	ds_read_b128 v[152:155], v156 offset:2048
	ds_read_b128 v[156:159], v156 offset:3072
	ds_read_b128 v[160:163], v178
	ds_read_b128 v[164:167], v178 offset:1024
	ds_read_b128 v[174:177], v178 offset:2048
	ds_read_b128 v[178:181], v178 offset:3072
	ds_read_b128 v[182:185], v171
	ds_read_b128 v[186:189], v171 offset:1024
	ds_read_b128 v[190:193], v171 offset:2048
	ds_read_b128 v[194:197], v171 offset:3072
	ds_read_b128 v[198:201], v171 offset:4096
	ds_read_b128 v[208:211], v171 offset:5120
	ds_read_b128 v[212:215], v171 offset:6144
	ds_read_b128 v[216:219], v171 offset:7168
	v_lshl_add_u64 v[202:203], s[40:41], 0, v[148:149]
	s_add_i32 m0, s53, 0xc000
	s_nop 0
	global_load_lds_dwordx4 v[202:203], off
	v_lshl_add_u64 v[202:203], s[40:41], 0, v[150:151]
	s_add_i32 m0, s53, 0xe000
	s_nop 0
	global_load_lds_dwordx4 v[202:203], off
	s_waitcnt vmcnt(8)
	s_waitcnt lgkmcnt(0)
	s_barrier
	s_setprio 1
	s_waitcnt lgkmcnt(0)
	v_mfma_f32_16x16x32_bf16 v[128:131], v[132:135], v[182:185], 0
	v_mfma_f32_16x16x32_bf16 v[128:131], v[136:139], v[186:189], v[128:131]
	v_mfma_f32_16x16x32_bf16 v[116:119], v[160:163], v[182:185], 0
	v_mfma_f32_16x16x32_bf16 v[116:119], v[164:167], v[186:189], v[116:119]
	v_mfma_f32_16x16x32_bf16 v[124:127], v[152:155], v[182:185], 0
	v_mfma_f32_16x16x32_bf16 v[124:127], v[156:159], v[186:189], v[124:127]
	v_mfma_f32_16x16x32_bf16 v[108:111], v[174:177], v[182:185], 0
	v_mfma_f32_16x16x32_bf16 v[108:111], v[178:181], v[186:189], v[108:111]
	v_mfma_f32_16x16x32_bf16 v[120:123], v[132:135], v[190:193], 0
	v_mfma_f32_16x16x32_bf16 v[120:123], v[136:139], v[194:197], v[120:123]
	v_mfma_f32_16x16x32_bf16 v[100:103], v[160:163], v[190:193], 0
	v_mfma_f32_16x16x32_bf16 v[100:103], v[164:167], v[194:197], v[100:103]
	v_mfma_f32_16x16x32_bf16 v[112:115], v[152:155], v[190:193], 0
	v_mfma_f32_16x16x32_bf16 v[112:115], v[156:159], v[194:197], v[112:115]
	v_mfma_f32_16x16x32_bf16 v[92:95], v[174:177], v[190:193], 0
	v_mfma_f32_16x16x32_bf16 v[92:95], v[178:181], v[194:197], v[92:95]
	v_mfma_f32_16x16x32_bf16 v[104:107], v[132:135], v[198:201], 0
	v_mfma_f32_16x16x32_bf16 v[104:107], v[136:139], v[208:211], v[104:107]
	v_mfma_f32_16x16x32_bf16 v[84:87], v[160:163], v[198:201], 0
	v_mfma_f32_16x16x32_bf16 v[84:87], v[164:167], v[208:211], v[84:87]
	v_mfma_f32_16x16x32_bf16 v[96:99], v[152:155], v[198:201], 0
	v_mfma_f32_16x16x32_bf16 v[96:99], v[156:159], v[208:211], v[96:99]
	v_mfma_f32_16x16x32_bf16 v[76:79], v[174:177], v[198:201], 0
	v_mfma_f32_16x16x32_bf16 v[76:79], v[178:181], v[208:211], v[76:79]
	v_mfma_f32_16x16x32_bf16 v[88:91], v[132:135], v[212:215], 0
	v_mfma_f32_16x16x32_bf16 v[88:91], v[136:139], v[216:219], v[88:91]
	v_mfma_f32_16x16x32_bf16 v[72:75], v[160:163], v[212:215], 0
	v_mfma_f32_16x16x32_bf16 v[72:75], v[164:167], v[216:219], v[72:75]
	v_mfma_f32_16x16x32_bf16 v[80:83], v[152:155], v[212:215], 0
	v_mfma_f32_16x16x32_bf16 v[80:83], v[156:159], v[216:219], v[80:83]
	v_mfma_f32_16x16x32_bf16 v[68:71], v[174:177], v[212:215], 0
	v_mfma_f32_16x16x32_bf16 v[68:71], v[178:181], v[216:219], v[68:71]
	s_setprio 0
	s_barrier
	s_sleep 2
	s_add_i32 s71, s71, s51
	v_lshl_add_u64 v[202:203], s[42:43], 0, v[2:3]
	s_mov_b32 m0, s71
	ds_read_b128 v[182:185], v171 offset:16384
	ds_read_b128 v[186:189], v171 offset:17408
	ds_read_b128 v[190:193], v171 offset:18432
	ds_read_b128 v[194:197], v171 offset:19456
	ds_read_b128 v[198:201], v171 offset:20480
	ds_read_b128 v[208:211], v171 offset:21504
	ds_read_b128 v[212:215], v171 offset:22528
	ds_read_b128 v[216:219], v171 offset:23552
	global_load_lds_dwordx4 v[202:203], off
	s_add_i32 m0, s71, 0x2000
	s_add_u32 s74, s42, 0x80000
	v_lshl_add_u64 v[204:205], s[42:43], 0, v[142:143]
	s_addc_u32 s75, s43, 0
	s_add_i32 s71, s73, s51
	global_load_lds_dwordx4 v[204:205], off
	v_lshl_add_u64 v[206:207], s[74:75], 0, v[2:3]
	s_mov_b32 m0, s71
	v_lshl_add_u64 v[220:221], s[44:45], 0, v[140:141]
	global_load_lds_dwordx4 v[206:207], off
	v_lshl_add_u64 v[206:207], s[74:75], 0, v[142:143]
	s_add_i32 m0, s71, 0x2000
	s_nop 0
	global_load_lds_dwordx4 v[206:207], off
	v_lshl_add_u64 v[206:207], s[44:45], 0, v[0:1]
	s_mov_b32 m0, s53
	s_nop 0
	global_load_lds_dwordx4 v[206:207], off
	s_mov_b32 m0, s54
	s_nop 0
	global_load_lds_dwordx4 v[220:221], off
	s_waitcnt vmcnt(8)
	s_waitcnt lgkmcnt(0)
	s_barrier
	s_setprio 1
	s_waitcnt lgkmcnt(0)
	v_mfma_f32_16x16x32_bf16 v[64:67], v[132:135], v[182:185], 0
	v_mfma_f32_16x16x32_bf16 v[64:67], v[136:139], v[186:189], v[64:67]
	v_mfma_f32_16x16x32_bf16 v[52:55], v[160:163], v[182:185], 0
	v_mfma_f32_16x16x32_bf16 v[52:55], v[164:167], v[186:189], v[52:55]
	v_mfma_f32_16x16x32_bf16 v[60:63], v[152:155], v[182:185], 0
	v_mfma_f32_16x16x32_bf16 v[60:63], v[156:159], v[186:189], v[60:63]
	v_mfma_f32_16x16x32_bf16 v[44:47], v[174:177], v[182:185], 0
	v_mfma_f32_16x16x32_bf16 v[44:47], v[178:181], v[186:189], v[44:47]
	v_mfma_f32_16x16x32_bf16 v[56:59], v[132:135], v[190:193], 0
	v_mfma_f32_16x16x32_bf16 v[56:59], v[136:139], v[194:197], v[56:59]
	v_mfma_f32_16x16x32_bf16 v[36:39], v[160:163], v[190:193], 0
	v_mfma_f32_16x16x32_bf16 v[36:39], v[164:167], v[194:197], v[36:39]
	v_mfma_f32_16x16x32_bf16 v[48:51], v[152:155], v[190:193], 0
	v_mfma_f32_16x16x32_bf16 v[48:51], v[156:159], v[194:197], v[48:51]
	v_mfma_f32_16x16x32_bf16 v[28:31], v[174:177], v[190:193], 0
	v_mfma_f32_16x16x32_bf16 v[28:31], v[178:181], v[194:197], v[28:31]
	v_mfma_f32_16x16x32_bf16 v[40:43], v[132:135], v[198:201], 0
	v_mfma_f32_16x16x32_bf16 v[40:43], v[136:139], v[208:211], v[40:43]
	v_mfma_f32_16x16x32_bf16 v[20:23], v[160:163], v[198:201], 0
	v_mfma_f32_16x16x32_bf16 v[20:23], v[164:167], v[208:211], v[20:23]
	v_mfma_f32_16x16x32_bf16 v[32:35], v[152:155], v[198:201], 0
	v_mfma_f32_16x16x32_bf16 v[32:35], v[156:159], v[208:211], v[32:35]
	v_mfma_f32_16x16x32_bf16 v[12:15], v[174:177], v[198:201], 0
	v_mfma_f32_16x16x32_bf16 v[12:15], v[178:181], v[208:211], v[12:15]
	v_mfma_f32_16x16x32_bf16 v[24:27], v[132:135], v[212:215], 0
	v_mfma_f32_16x16x32_bf16 v[24:27], v[136:139], v[216:219], v[24:27]
	v_mfma_f32_16x16x32_bf16 v[8:11], v[160:163], v[212:215], 0
	v_mfma_f32_16x16x32_bf16 v[8:11], v[164:167], v[216:219], v[8:11]
	v_mfma_f32_16x16x32_bf16 v[16:19], v[152:155], v[212:215], 0
	v_mfma_f32_16x16x32_bf16 v[16:19], v[156:159], v[216:219], v[16:19]
	v_mfma_f32_16x16x32_bf16 v[4:7], v[174:177], v[212:215], 0
	v_mfma_f32_16x16x32_bf16 v[4:7], v[178:181], v[216:219], v[4:7]
	s_setprio 0
	s_barrier
	s_sleep 1
	s_add_i32 s71, 0, 0x18000
	s_add_i32 s73, 0, 0x1c000
	s_add_u32 s44, s44, 0x80000
	s_addc_u32 s45, s45, 0
	s_mov_b32 m0, s55
	v_lshl_add_u64 v[222:223], s[44:45], 0, v[0:1]
	global_load_lds_dwordx4 v[222:223], off
	v_lshl_add_u64 v[222:223], s[44:45], 0, v[140:141]
	s_mov_b32 m0, s56
	s_nop 0
	global_load_lds_dwordx4 v[222:223], off
	v_add_u32_e32 v156, s71, v169
	v_add_u32_e32 v178, s73, v169
	ds_read_b128 v[132:135], v156
	ds_read_b128 v[136:139], v156 offset:1024
	ds_read_b128 v[152:155], v156 offset:2048
	ds_read_b128 v[156:159], v156 offset:3072
	ds_read_b128 v[160:163], v178
	ds_read_b128 v[164:167], v178 offset:1024
	ds_read_b128 v[174:177], v178 offset:2048
	ds_read_b128 v[178:181], v178 offset:3072
	ds_read_b128 v[182:185], v171 offset:32768
	ds_read_b128 v[186:189], v171 offset:33792
	ds_read_b128 v[190:193], v171 offset:34816
	ds_read_b128 v[194:197], v171 offset:35840
	ds_read_b128 v[198:201], v171 offset:36864
	ds_read_b128 v[208:211], v171 offset:37888
	ds_read_b128 v[212:215], v171 offset:38912
	ds_read_b128 v[216:219], v171 offset:39936
	s_waitcnt vmcnt(8)
	s_waitcnt lgkmcnt(0)
	s_barrier
	s_setprio 1
	s_waitcnt lgkmcnt(0)
	v_mfma_f32_16x16x32_bf16 v[128:131], v[132:135], v[182:185], v[128:131]
	v_mfma_f32_16x16x32_bf16 v[128:131], v[136:139], v[186:189], v[128:131]
	v_mfma_f32_16x16x32_bf16 v[116:119], v[160:163], v[182:185], v[116:119]
	v_mfma_f32_16x16x32_bf16 v[116:119], v[164:167], v[186:189], v[116:119]
	v_mfma_f32_16x16x32_bf16 v[124:127], v[152:155], v[182:185], v[124:127]
	v_mfma_f32_16x16x32_bf16 v[124:127], v[156:159], v[186:189], v[124:127]
	v_mfma_f32_16x16x32_bf16 v[108:111], v[174:177], v[182:185], v[108:111]
	v_mfma_f32_16x16x32_bf16 v[108:111], v[178:181], v[186:189], v[108:111]
	v_mfma_f32_16x16x32_bf16 v[120:123], v[132:135], v[190:193], v[120:123]
	v_mfma_f32_16x16x32_bf16 v[120:123], v[136:139], v[194:197], v[120:123]
	v_mfma_f32_16x16x32_bf16 v[100:103], v[160:163], v[190:193], v[100:103]
	v_mfma_f32_16x16x32_bf16 v[100:103], v[164:167], v[194:197], v[100:103]
	v_mfma_f32_16x16x32_bf16 v[112:115], v[152:155], v[190:193], v[112:115]
	v_mfma_f32_16x16x32_bf16 v[112:115], v[156:159], v[194:197], v[112:115]
	v_mfma_f32_16x16x32_bf16 v[92:95], v[174:177], v[190:193], v[92:95]
	v_mfma_f32_16x16x32_bf16 v[92:95], v[178:181], v[194:197], v[92:95]
	v_mfma_f32_16x16x32_bf16 v[104:107], v[132:135], v[198:201], v[104:107]
	v_mfma_f32_16x16x32_bf16 v[104:107], v[136:139], v[208:211], v[104:107]
	v_mfma_f32_16x16x32_bf16 v[84:87], v[160:163], v[198:201], v[84:87]
	v_mfma_f32_16x16x32_bf16 v[84:87], v[164:167], v[208:211], v[84:87]
	v_mfma_f32_16x16x32_bf16 v[96:99], v[152:155], v[198:201], v[96:99]
	v_mfma_f32_16x16x32_bf16 v[96:99], v[156:159], v[208:211], v[96:99]
	v_mfma_f32_16x16x32_bf16 v[76:79], v[174:177], v[198:201], v[76:79]
	v_mfma_f32_16x16x32_bf16 v[76:79], v[178:181], v[208:211], v[76:79]
	v_mfma_f32_16x16x32_bf16 v[88:91], v[132:135], v[212:215], v[88:91]
	v_mfma_f32_16x16x32_bf16 v[88:91], v[136:139], v[216:219], v[88:91]
	v_mfma_f32_16x16x32_bf16 v[72:75], v[160:163], v[212:215], v[72:75]
	v_mfma_f32_16x16x32_bf16 v[72:75], v[164:167], v[216:219], v[72:75]
	v_mfma_f32_16x16x32_bf16 v[80:83], v[152:155], v[212:215], v[80:83]
	v_mfma_f32_16x16x32_bf16 v[80:83], v[156:159], v[216:219], v[80:83]
	v_mfma_f32_16x16x32_bf16 v[68:71], v[174:177], v[212:215], v[68:71]
	v_mfma_f32_16x16x32_bf16 v[68:71], v[178:181], v[216:219], v[68:71]
	s_setprio 0
	s_barrier
	s_sleep 2
	s_add_i32 s44, s71, s51
	v_lshl_add_u64 v[202:203], v[202:203], 0, s[66:67]
	s_mov_b32 m0, s44
	ds_read_b128 v[182:185], v171 offset:49152
	ds_read_b128 v[186:189], v171 offset:50176
	ds_read_b128 v[190:193], v171 offset:51200
	ds_read_b128 v[194:197], v171 offset:52224
	ds_read_b128 v[198:201], v171 offset:53248
	ds_read_b128 v[208:211], v171 offset:54272
	ds_read_b128 v[212:215], v171 offset:55296
	ds_read_b128 v[216:219], v171 offset:56320
	global_load_lds_dwordx4 v[202:203], off
	s_add_i32 m0, s44, 0x2000
	s_add_u32 s42, s42, 0x80080
	v_lshl_add_u64 v[202:203], v[204:205], 0, s[66:67]
	s_addc_u32 s43, s43, 0
	s_add_i32 s44, s73, s51
	global_load_lds_dwordx4 v[202:203], off
	v_lshl_add_u64 v[202:203], s[42:43], 0, v[2:3]
	s_mov_b32 m0, s44
	s_nop 0
	global_load_lds_dwordx4 v[202:203], off
	v_lshl_add_u64 v[202:203], s[42:43], 0, v[142:143]
	s_add_i32 m0, s44, 0x2000
	s_nop 0
	global_load_lds_dwordx4 v[202:203], off
	v_lshl_add_u64 v[202:203], v[206:207], 0, s[66:67]
	s_mov_b32 m0, s65
	s_nop 0
	global_load_lds_dwordx4 v[202:203], off
	v_lshl_add_u64 v[202:203], v[220:221], 0, s[66:67]
	s_mov_b32 m0, s68
	s_nop 0
	global_load_lds_dwordx4 v[202:203], off
	s_waitcnt vmcnt(8)
	s_waitcnt lgkmcnt(0)
	s_barrier
	s_setprio 1
	s_waitcnt lgkmcnt(0)
	v_mfma_f32_16x16x32_bf16 v[64:67], v[132:135], v[182:185], v[64:67]
	v_mfma_f32_16x16x32_bf16 v[64:67], v[136:139], v[186:189], v[64:67]
	v_mfma_f32_16x16x32_bf16 v[52:55], v[160:163], v[182:185], v[52:55]
	v_mfma_f32_16x16x32_bf16 v[52:55], v[164:167], v[186:189], v[52:55]
	v_mfma_f32_16x16x32_bf16 v[60:63], v[152:155], v[182:185], v[60:63]
	v_mfma_f32_16x16x32_bf16 v[60:63], v[156:159], v[186:189], v[60:63]
	v_mfma_f32_16x16x32_bf16 v[44:47], v[174:177], v[182:185], v[44:47]
	v_mfma_f32_16x16x32_bf16 v[44:47], v[178:181], v[186:189], v[44:47]
	v_mfma_f32_16x16x32_bf16 v[56:59], v[132:135], v[190:193], v[56:59]
	v_mfma_f32_16x16x32_bf16 v[56:59], v[136:139], v[194:197], v[56:59]
	v_mfma_f32_16x16x32_bf16 v[36:39], v[160:163], v[190:193], v[36:39]
	v_mfma_f32_16x16x32_bf16 v[36:39], v[164:167], v[194:197], v[36:39]
	v_mfma_f32_16x16x32_bf16 v[48:51], v[152:155], v[190:193], v[48:51]
	v_mfma_f32_16x16x32_bf16 v[48:51], v[156:159], v[194:197], v[48:51]
	v_mfma_f32_16x16x32_bf16 v[28:31], v[174:177], v[190:193], v[28:31]
	v_mfma_f32_16x16x32_bf16 v[28:31], v[178:181], v[194:197], v[28:31]
	v_mfma_f32_16x16x32_bf16 v[40:43], v[132:135], v[198:201], v[40:43]
	v_mfma_f32_16x16x32_bf16 v[40:43], v[136:139], v[208:211], v[40:43]
	v_mfma_f32_16x16x32_bf16 v[20:23], v[160:163], v[198:201], v[20:23]
	v_mfma_f32_16x16x32_bf16 v[20:23], v[164:167], v[208:211], v[20:23]
	v_mfma_f32_16x16x32_bf16 v[32:35], v[152:155], v[198:201], v[32:35]
	v_mfma_f32_16x16x32_bf16 v[32:35], v[156:159], v[208:211], v[32:35]
	v_mfma_f32_16x16x32_bf16 v[12:15], v[174:177], v[198:201], v[12:15]
	v_mfma_f32_16x16x32_bf16 v[12:15], v[178:181], v[208:211], v[12:15]
	v_mfma_f32_16x16x32_bf16 v[24:27], v[132:135], v[212:215], v[24:27]
	v_mfma_f32_16x16x32_bf16 v[24:27], v[136:139], v[216:219], v[24:27]
	v_mfma_f32_16x16x32_bf16 v[8:11], v[160:163], v[212:215], v[8:11]
	v_mfma_f32_16x16x32_bf16 v[8:11], v[164:167], v[216:219], v[8:11]
	v_mfma_f32_16x16x32_bf16 v[16:19], v[152:155], v[212:215], v[16:19]
	v_mfma_f32_16x16x32_bf16 v[16:19], v[156:159], v[216:219], v[16:19]
	v_mfma_f32_16x16x32_bf16 v[4:7], v[174:177], v[212:215], v[4:7]
	v_mfma_f32_16x16x32_bf16 v[4:7], v[178:181], v[216:219], v[4:7]
	s_setprio 0
	s_barrier
	s_add_i32 s63, s63, 2
	s_add_u32 s40, s40, 0x100
	s_addc_u32 s41, s41, 0
	s_add_u32 s31, s31, 0x100
	s_addc_u32 s62, s62, 0
	s_cmp_gt_u32 s63, 29

.LBB0_210:
	s_ashr_i32 s21, s20, 31
	s_lshl_b64 s[22:23], s[20:21], 20
	s_add_u32 s22, s4, s22
	s_addc_u32 s23, s5, s23
	s_and_b64 s[24:25], s[34:35], exec
	s_cselect_b32 s21, s23, s29
	s_cselect_b32 s53, s22, s28
	s_ashr_i32 s19, s18, 31
	s_lshl_b64 s[24:25], s[18:19], 20
	s_add_u32 s24, s2, s24
	s_addc_u32 s25, s40, s25
	s_and_b64 s[38:39], s[34:35], exec
	s_cselect_b32 s19, s25, s31
	s_cselect_b32 s54, s24, s30
	s_add_u32 s28, s28, 0x80080
	s_addc_u32 s29, s29, 0
	s_add_u32 s55, s30, 0x100
	s_addc_u32 s56, s31, 0
	s_mov_b32 s57, -2
	s_add_u32 s30, s28, 0xfff80080
	s_addc_u32 s31, s29, -1
	s_add_i32 s58, 0, 0x10000
	s_cmp_eq_u32 s57, 28
	s_cselect_b32 s39, s21, s31
	s_cselect_b32 s38, s53, s30
	s_cselect_b32 s31, s19, s56
	s_cselect_b32 s30, s54, s55
	s_add_i32 s60, 0, 0x14000
	v_add_u32_e32 v148, s58, v151
	ds_read_b128 v[140:143], v148
	ds_read_b128 v[144:147], v148 offset:1024
	ds_read_b128 v[156:159], v148 offset:2048
	ds_read_b128 v[160:163], v148 offset:3072
	v_add_u32_e32 v148, s60, v151
	ds_read_b128 v[164:167], v148
	ds_read_b128 v[168:171], v148 offset:1024
	ds_read_b128 v[172:175], v148 offset:2048
	ds_read_b128 v[176:179], v148 offset:3072
	ds_read_b128 v[180:183], v154
	ds_read_b128 v[184:187], v154 offset:1024
	ds_read_b128 v[188:191], v154 offset:2048
	ds_read_b128 v[192:195], v154 offset:3072
	ds_read_b128 v[196:199], v154 offset:4096
	ds_read_b128 v[200:203], v154 offset:5120
	ds_read_b128 v[208:211], v154 offset:6144
	ds_read_b128 v[212:215], v154 offset:7168
	s_add_i32 m0, s43, 0xc000
	s_nop 0
	global_load_lds_dwordx4 v136, s[28:29]
	s_add_i32 m0, s43, 0xe000
	s_nop 0
	global_load_lds_dwordx4 v138, s[28:29]
	s_waitcnt vmcnt(8)
	s_waitcnt lgkmcnt(0)
	s_barrier
	s_setprio 1
	s_waitcnt lgkmcnt(0)
	v_mfma_f32_16x16x32_bf16 v[128:131], v[140:143], v[180:183], 0
	v_mfma_f32_16x16x32_bf16 v[128:131], v[144:147], v[184:187], v[128:131]
	v_mfma_f32_16x16x32_bf16 v[120:123], v[164:167], v[180:183], 0
	v_mfma_f32_16x16x32_bf16 v[120:123], v[168:171], v[184:187], v[120:123]
	v_mfma_f32_16x16x32_bf16 v[124:127], v[156:159], v[180:183], 0
	v_mfma_f32_16x16x32_bf16 v[124:127], v[160:163], v[184:187], v[124:127]
	v_mfma_f32_16x16x32_bf16 v[116:119], v[172:175], v[180:183], 0
	v_mfma_f32_16x16x32_bf16 v[116:119], v[176:179], v[184:187], v[116:119]
	v_mfma_f32_16x16x32_bf16 v[112:115], v[140:143], v[188:191], 0
	v_mfma_f32_16x16x32_bf16 v[112:115], v[144:147], v[192:195], v[112:115]
	v_mfma_f32_16x16x32_bf16 v[104:107], v[164:167], v[188:191], 0
	v_mfma_f32_16x16x32_bf16 v[104:107], v[168:171], v[192:195], v[104:107]
	v_mfma_f32_16x16x32_bf16 v[108:111], v[156:159], v[188:191], 0
	v_mfma_f32_16x16x32_bf16 v[108:111], v[160:163], v[192:195], v[108:111]
	v_mfma_f32_16x16x32_bf16 v[100:103], v[172:175], v[188:191], 0
	v_mfma_f32_16x16x32_bf16 v[100:103], v[176:179], v[192:195], v[100:103]
	v_mfma_f32_16x16x32_bf16 v[96:99], v[140:143], v[196:199], 0
	v_mfma_f32_16x16x32_bf16 v[96:99], v[144:147], v[200:203], v[96:99]
	v_mfma_f32_16x16x32_bf16 v[88:91], v[164:167], v[196:199], 0
	v_mfma_f32_16x16x32_bf16 v[88:91], v[168:171], v[200:203], v[88:91]
	v_mfma_f32_16x16x32_bf16 v[92:95], v[156:159], v[196:199], 0
	v_mfma_f32_16x16x32_bf16 v[92:95], v[160:163], v[200:203], v[92:95]
	v_mfma_f32_16x16x32_bf16 v[84:87], v[172:175], v[196:199], 0
	v_mfma_f32_16x16x32_bf16 v[84:87], v[176:179], v[200:203], v[84:87]
	v_mfma_f32_16x16x32_bf16 v[80:83], v[140:143], v[208:211], 0
	v_mfma_f32_16x16x32_bf16 v[80:83], v[144:147], v[212:215], v[80:83]
	v_mfma_f32_16x16x32_bf16 v[72:75], v[164:167], v[208:211], 0
	v_mfma_f32_16x16x32_bf16 v[72:75], v[168:171], v[212:215], v[72:75]
	v_mfma_f32_16x16x32_bf16 v[76:79], v[156:159], v[208:211], 0
	v_mfma_f32_16x16x32_bf16 v[76:79], v[160:163], v[212:215], v[76:79]
	v_mfma_f32_16x16x32_bf16 v[68:71], v[172:175], v[208:211], 0
	v_mfma_f32_16x16x32_bf16 v[68:71], v[176:179], v[212:215], v[68:71]
	s_setprio 0
	s_barrier
	s_sleep 2
	s_add_i32 s58, s58, s41
	s_mov_b32 m0, s58
	ds_read_b128 v[180:183], v154 offset:16384
	ds_read_b128 v[184:187], v154 offset:17408
	ds_read_b128 v[188:191], v154 offset:18432
	ds_read_b128 v[192:195], v154 offset:19456
	ds_read_b128 v[196:199], v154 offset:20480
	ds_read_b128 v[200:203], v154 offset:21504
	ds_read_b128 v[208:211], v154 offset:22528
	ds_read_b128 v[212:215], v154 offset:23552
	global_load_lds_dwordx4 v2, s[30:31]
	s_add_i32 m0, s58, 0x2000
	s_add_u32 s62, s30, 0x80000
	s_addc_u32 s63, s31, 0
	s_add_i32 s58, s60, s41
	global_load_lds_dwordx4 v0, s[30:31]
	s_mov_b32 m0, s58
	s_nop 0
	global_load_lds_dwordx4 v2, s[62:63]
	s_add_i32 m0, s58, 0x2000
	s_nop 0
	global_load_lds_dwordx4 v0, s[62:63]
	s_mov_b32 m0, s43
	s_nop 0
	global_load_lds_dwordx4 v134, s[38:39]
	s_mov_b32 m0, s44
	s_nop 0
	global_load_lds_dwordx4 v132, s[38:39]
	s_waitcnt vmcnt(8)
	s_waitcnt lgkmcnt(0)
	s_barrier
	s_setprio 1
	s_waitcnt lgkmcnt(0)
	v_mfma_f32_16x16x32_bf16 v[64:67], v[140:143], v[180:183], 0
	v_mfma_f32_16x16x32_bf16 v[64:67], v[144:147], v[184:187], v[64:67]
	v_mfma_f32_16x16x32_bf16 v[56:59], v[164:167], v[180:183], 0
	v_mfma_f32_16x16x32_bf16 v[56:59], v[168:171], v[184:187], v[56:59]
	v_mfma_f32_16x16x32_bf16 v[60:63], v[156:159], v[180:183], 0
	v_mfma_f32_16x16x32_bf16 v[60:63], v[160:163], v[184:187], v[60:63]
	v_mfma_f32_16x16x32_bf16 v[52:55], v[172:175], v[180:183], 0
	v_mfma_f32_16x16x32_bf16 v[52:55], v[176:179], v[184:187], v[52:55]
	v_mfma_f32_16x16x32_bf16 v[48:51], v[140:143], v[188:191], 0
	v_mfma_f32_16x16x32_bf16 v[48:51], v[144:147], v[192:195], v[48:51]
	v_mfma_f32_16x16x32_bf16 v[40:43], v[164:167], v[188:191], 0
	v_mfma_f32_16x16x32_bf16 v[40:43], v[168:171], v[192:195], v[40:43]
	v_mfma_f32_16x16x32_bf16 v[44:47], v[156:159], v[188:191], 0
	v_mfma_f32_16x16x32_bf16 v[44:47], v[160:163], v[192:195], v[44:47]
	v_mfma_f32_16x16x32_bf16 v[36:39], v[172:175], v[188:191], 0
	v_mfma_f32_16x16x32_bf16 v[36:39], v[176:179], v[192:195], v[36:39]
	v_mfma_f32_16x16x32_bf16 v[32:35], v[140:143], v[196:199], 0
	v_mfma_f32_16x16x32_bf16 v[32:35], v[144:147], v[200:203], v[32:35]
	v_mfma_f32_16x16x32_bf16 v[24:27], v[164:167], v[196:199], 0
	v_mfma_f32_16x16x32_bf16 v[24:27], v[168:171], v[200:203], v[24:27]
	v_mfma_f32_16x16x32_bf16 v[28:31], v[156:159], v[196:199], 0
	v_mfma_f32_16x16x32_bf16 v[28:31], v[160:163], v[200:203], v[28:31]
	v_mfma_f32_16x16x32_bf16 v[20:23], v[172:175], v[196:199], 0
	v_mfma_f32_16x16x32_bf16 v[20:23], v[176:179], v[200:203], v[20:23]
	v_mfma_f32_16x16x32_bf16 v[16:19], v[140:143], v[208:211], 0
	v_mfma_f32_16x16x32_bf16 v[16:19], v[144:147], v[212:215], v[16:19]
	v_mfma_f32_16x16x32_bf16 v[8:11], v[164:167], v[208:211], 0
	v_mfma_f32_16x16x32_bf16 v[8:11], v[168:171], v[212:215], v[8:11]
	v_mfma_f32_16x16x32_bf16 v[12:15], v[156:159], v[208:211], 0
	v_mfma_f32_16x16x32_bf16 v[12:15], v[160:163], v[212:215], v[12:15]
	v_mfma_f32_16x16x32_bf16 v[4:7], v[172:175], v[208:211], 0
	v_mfma_f32_16x16x32_bf16 v[4:7], v[176:179], v[212:215], v[4:7]
	s_setprio 0
	s_barrier
	s_sleep 1
	s_add_i32 s58, 0, 0x18000
	s_add_i32 s60, 0, 0x1c000
	s_add_u32 s38, s38, 0x80000
	s_addc_u32 s39, s39, 0
	s_mov_b32 m0, s45
	s_nop 0
	global_load_lds_dwordx4 v134, s[38:39]
	s_mov_b32 m0, s47
	s_nop 0
	global_load_lds_dwordx4 v132, s[38:39]
	v_add_u32_e32 v155, s58, v151
	ds_read_b128 v[140:143], v155
	ds_read_b128 v[144:147], v155 offset:1024
	ds_read_b128 v[156:159], v155 offset:2048
	ds_read_b128 v[160:163], v155 offset:3072
	v_add_u32_e32 v155, s60, v151
	ds_read_b128 v[164:167], v155
	ds_read_b128 v[168:171], v155 offset:1024
	ds_read_b128 v[172:175], v155 offset:2048
	ds_read_b128 v[176:179], v155 offset:3072
	ds_read_b128 v[180:183], v154 offset:32768
	ds_read_b128 v[184:187], v154 offset:33792
	ds_read_b128 v[188:191], v154 offset:34816
	ds_read_b128 v[192:195], v154 offset:35840
	ds_read_b128 v[196:199], v154 offset:36864
	ds_read_b128 v[200:203], v154 offset:37888
	ds_read_b128 v[208:211], v154 offset:38912
	ds_read_b128 v[212:215], v154 offset:39936
	s_waitcnt vmcnt(8)
	s_waitcnt lgkmcnt(0)
	s_barrier
	s_setprio 1
	s_waitcnt lgkmcnt(0)
	v_mfma_f32_16x16x32_bf16 v[128:131], v[140:143], v[180:183], v[128:131]
	v_mfma_f32_16x16x32_bf16 v[128:131], v[144:147], v[184:187], v[128:131]
	v_mfma_f32_16x16x32_bf16 v[120:123], v[164:167], v[180:183], v[120:123]
	v_mfma_f32_16x16x32_bf16 v[120:123], v[168:171], v[184:187], v[120:123]
	v_mfma_f32_16x16x32_bf16 v[124:127], v[156:159], v[180:183], v[124:127]
	v_mfma_f32_16x16x32_bf16 v[124:127], v[160:163], v[184:187], v[124:127]
	v_mfma_f32_16x16x32_bf16 v[116:119], v[172:175], v[180:183], v[116:119]
	v_mfma_f32_16x16x32_bf16 v[116:119], v[176:179], v[184:187], v[116:119]
	v_mfma_f32_16x16x32_bf16 v[112:115], v[140:143], v[188:191], v[112:115]
	v_mfma_f32_16x16x32_bf16 v[112:115], v[144:147], v[192:195], v[112:115]
	v_mfma_f32_16x16x32_bf16 v[104:107], v[164:167], v[188:191], v[104:107]
	v_mfma_f32_16x16x32_bf16 v[104:107], v[168:171], v[192:195], v[104:107]
	v_mfma_f32_16x16x32_bf16 v[108:111], v[156:159], v[188:191], v[108:111]
	v_mfma_f32_16x16x32_bf16 v[108:111], v[160:163], v[192:195], v[108:111]
	v_mfma_f32_16x16x32_bf16 v[100:103], v[172:175], v[188:191], v[100:103]
	v_mfma_f32_16x16x32_bf16 v[100:103], v[176:179], v[192:195], v[100:103]
	v_mfma_f32_16x16x32_bf16 v[96:99], v[140:143], v[196:199], v[96:99]
	v_mfma_f32_16x16x32_bf16 v[96:99], v[144:147], v[200:203], v[96:99]
	v_mfma_f32_16x16x32_bf16 v[88:91], v[164:167], v[196:199], v[88:91]
	v_mfma_f32_16x16x32_bf16 v[88:91], v[168:171], v[200:203], v[88:91]
	v_mfma_f32_16x16x32_bf16 v[92:95], v[156:159], v[196:199], v[92:95]
	v_mfma_f32_16x16x32_bf16 v[92:95], v[160:163], v[200:203], v[92:95]
	v_mfma_f32_16x16x32_bf16 v[84:87], v[172:175], v[196:199], v[84:87]
	v_mfma_f32_16x16x32_bf16 v[84:87], v[176:179], v[200:203], v[84:87]
	v_mfma_f32_16x16x32_bf16 v[80:83], v[140:143], v[208:211], v[80:83]
	v_mfma_f32_16x16x32_bf16 v[80:83], v[144:147], v[212:215], v[80:83]
	v_mfma_f32_16x16x32_bf16 v[72:75], v[164:167], v[208:211], v[72:75]
	v_mfma_f32_16x16x32_bf16 v[72:75], v[168:171], v[212:215], v[72:75]
	v_mfma_f32_16x16x32_bf16 v[76:79], v[156:159], v[208:211], v[76:79]
	v_mfma_f32_16x16x32_bf16 v[76:79], v[160:163], v[212:215], v[76:79]
	v_mfma_f32_16x16x32_bf16 v[68:71], v[172:175], v[208:211], v[68:71]
	v_mfma_f32_16x16x32_bf16 v[68:71], v[176:179], v[212:215], v[68:71]
	s_setprio 0
	s_barrier
	s_sleep 2
	s_add_i32 s62, s58, s41
	s_add_u32 s30, s30, 0x80
	s_addc_u32 s31, s31, 0
	s_mov_b32 m0, s62
	ds_read_b128 v[180:183], v154 offset:49152
	ds_read_b128 v[184:187], v154 offset:50176
	ds_read_b128 v[188:191], v154 offset:51200
	ds_read_b128 v[192:195], v154 offset:52224
	ds_read_b128 v[196:199], v154 offset:53248
	ds_read_b128 v[200:203], v154 offset:54272
	ds_read_b128 v[208:211], v154 offset:55296
	ds_read_b128 v[212:215], v154 offset:56320
	global_load_lds_dwordx4 v2, s[30:31]
	s_add_i32 m0, s62, 0x2000
	s_nop 0
	s_add_i32 s62, s60, s41
	global_load_lds_dwordx4 v0, s[30:31]
	s_add_u32 s30, s30, 0x80000
	s_addc_u32 s31, s31, 0
	s_mov_b32 m0, s62
	s_nop 0
	global_load_lds_dwordx4 v2, s[30:31]
	s_add_i32 m0, s62, 0x2000
	s_nop 0
	global_load_lds_dwordx4 v0, s[30:31]
	s_sub_u32 s38, s38, 0x7ff80
	s_subb_u32 s39, s39, 0
	s_mov_b32 m0, s48
	s_nop 0
	global_load_lds_dwordx4 v134, s[38:39]
	s_mov_b32 m0, s49
	s_nop 0
	global_load_lds_dwordx4 v132, s[38:39]
	s_waitcnt vmcnt(8)
	s_waitcnt lgkmcnt(0)
	s_barrier
	s_setprio 1
	s_waitcnt lgkmcnt(0)
	v_mfma_f32_16x16x32_bf16 v[64:67], v[140:143], v[180:183], v[64:67]
	v_mfma_f32_16x16x32_bf16 v[64:67], v[144:147], v[184:187], v[64:67]
	v_mfma_f32_16x16x32_bf16 v[56:59], v[164:167], v[180:183], v[56:59]
	v_mfma_f32_16x16x32_bf16 v[56:59], v[168:171], v[184:187], v[56:59]
	v_mfma_f32_16x16x32_bf16 v[60:63], v[156:159], v[180:183], v[60:63]
	v_mfma_f32_16x16x32_bf16 v[60:63], v[160:163], v[184:187], v[60:63]
	v_mfma_f32_16x16x32_bf16 v[52:55], v[172:175], v[180:183], v[52:55]
	v_mfma_f32_16x16x32_bf16 v[52:55], v[176:179], v[184:187], v[52:55]
	v_mfma_f32_16x16x32_bf16 v[48:51], v[140:143], v[188:191], v[48:51]
	v_mfma_f32_16x16x32_bf16 v[48:51], v[144:147], v[192:195], v[48:51]
	v_mfma_f32_16x16x32_bf16 v[40:43], v[164:167], v[188:191], v[40:43]
	v_mfma_f32_16x16x32_bf16 v[40:43], v[168:171], v[192:195], v[40:43]
	v_mfma_f32_16x16x32_bf16 v[44:47], v[156:159], v[188:191], v[44:47]
	v_mfma_f32_16x16x32_bf16 v[44:47], v[160:163], v[192:195], v[44:47]
	v_mfma_f32_16x16x32_bf16 v[36:39], v[172:175], v[188:191], v[36:39]
	v_mfma_f32_16x16x32_bf16 v[36:39], v[176:179], v[192:195], v[36:39]
	v_mfma_f32_16x16x32_bf16 v[32:35], v[140:143], v[196:199], v[32:35]
	v_mfma_f32_16x16x32_bf16 v[32:35], v[144:147], v[200:203], v[32:35]
	v_mfma_f32_16x16x32_bf16 v[24:27], v[164:167], v[196:199], v[24:27]
	v_mfma_f32_16x16x32_bf16 v[24:27], v[168:171], v[200:203], v[24:27]
	v_mfma_f32_16x16x32_bf16 v[28:31], v[156:159], v[196:199], v[28:31]
	v_mfma_f32_16x16x32_bf16 v[28:31], v[160:163], v[200:203], v[28:31]
	v_mfma_f32_16x16x32_bf16 v[20:23], v[172:175], v[196:199], v[20:23]
	v_mfma_f32_16x16x32_bf16 v[20:23], v[176:179], v[200:203], v[20:23]
	v_mfma_f32_16x16x32_bf16 v[16:19], v[140:143], v[208:211], v[16:19]
	v_mfma_f32_16x16x32_bf16 v[16:19], v[144:147], v[212:215], v[16:19]
	v_mfma_f32_16x16x32_bf16 v[8:11], v[164:167], v[208:211], v[8:11]
	v_mfma_f32_16x16x32_bf16 v[8:11], v[168:171], v[212:215], v[8:11]
	v_mfma_f32_16x16x32_bf16 v[12:15], v[156:159], v[208:211], v[12:15]
	v_mfma_f32_16x16x32_bf16 v[12:15], v[160:163], v[212:215], v[12:15]
	v_mfma_f32_16x16x32_bf16 v[4:7], v[172:175], v[208:211], v[4:7]
	v_mfma_f32_16x16x32_bf16 v[4:7], v[176:179], v[212:215], v[4:7]
	s_setprio 0
	s_barrier
	s_add_i32 s57, s57, 2
	s_add_u32 s28, s28, 0x100
	s_addc_u32 s29, s29, 0
	s_add_u32 s55, s55, 0x100
	s_addc_u32 s56, s56, 0
	s_cmp_gt_u32 s57, 29

.LBB0_300:
	s_add_u32 s40, s18, 0x100
	s_addc_u32 s41, s19, 0
	s_mov_b32 s48, -2
	s_add_u32 s18, s16, 0x100
	s_addc_u32 s19, s17, 0
	s_add_i32 s49, 0, 0x10000
	s_cmpk_eq_i32 s48, 0x54
	s_cselect_b32 s23, s13, s19
	s_cselect_b32 s22, s12, s18
	s_cselect_b32 s21, s15, s41
	s_cselect_b32 s20, s14, s40
	s_add_i32 s50, 0, 0x14000
	v_add_u32_e32 v144, s49, v219
	v_add_u32_e32 v160, s50, v219
	ds_read_b128 v[124:127], v144
	ds_read_b128 v[128:131], v144 offset:1024
	ds_read_b128 v[140:143], v144 offset:2048
	ds_read_b128 v[144:147], v144 offset:3072
	ds_read_b128 v[148:151], v160
	ds_read_b128 v[152:155], v160 offset:1024
	ds_read_b128 v[156:159], v160 offset:2048
	ds_read_b128 v[160:163], v160 offset:3072
	ds_read_b128 v[164:167], v221
	ds_read_b128 v[168:171], v221 offset:1024
	ds_read_b128 v[172:175], v221 offset:2048
	ds_read_b128 v[176:179], v221 offset:3072
	ds_read_b128 v[180:183], v221 offset:4096
	ds_read_b128 v[184:187], v221 offset:5120
	ds_read_b128 v[196:199], v221 offset:6144
	ds_read_b128 v[200:203], v221 offset:7168
	v_lshl_add_u64 v[204:205], s[16:17], 0, v[192:193]
	s_add_i32 m0, s28, 0xc000
	s_nop 0
	global_load_lds_dwordx4 v[204:205], off
	v_lshl_add_u64 v[204:205], s[16:17], 0, v[194:195]
	s_add_i32 m0, s28, 0xe000
	s_nop 0
	global_load_lds_dwordx4 v[204:205], off
	s_waitcnt vmcnt(8)
	s_waitcnt lgkmcnt(0)
	s_barrier
	s_setprio 1
	s_waitcnt lgkmcnt(0)
	v_mfma_f32_16x16x32_bf16 v[136:139], v[124:127], v[164:167], 0
	v_mfma_f32_16x16x32_bf16 v[136:139], v[128:131], v[168:171], v[136:139]
	v_mfma_f32_16x16x32_bf16 v[120:123], v[148:151], v[164:167], 0
	v_mfma_f32_16x16x32_bf16 v[120:123], v[152:155], v[168:171], v[120:123]
	v_mfma_f32_16x16x32_bf16 v[132:135], v[140:143], v[164:167], 0
	v_mfma_f32_16x16x32_bf16 v[132:135], v[144:147], v[168:171], v[132:135]
	v_mfma_f32_16x16x32_bf16 v[116:119], v[156:159], v[164:167], 0
	v_mfma_f32_16x16x32_bf16 v[116:119], v[160:163], v[168:171], v[116:119]
	v_mfma_f32_16x16x32_bf16 v[112:115], v[124:127], v[172:175], 0
	v_mfma_f32_16x16x32_bf16 v[112:115], v[128:131], v[176:179], v[112:115]
	v_mfma_f32_16x16x32_bf16 v[104:107], v[148:151], v[172:175], 0
	v_mfma_f32_16x16x32_bf16 v[104:107], v[152:155], v[176:179], v[104:107]
	v_mfma_f32_16x16x32_bf16 v[108:111], v[140:143], v[172:175], 0
	v_mfma_f32_16x16x32_bf16 v[108:111], v[144:147], v[176:179], v[108:111]
	v_mfma_f32_16x16x32_bf16 v[100:103], v[156:159], v[172:175], 0
	v_mfma_f32_16x16x32_bf16 v[100:103], v[160:163], v[176:179], v[100:103]
	v_mfma_f32_16x16x32_bf16 v[96:99], v[124:127], v[180:183], 0
	v_mfma_f32_16x16x32_bf16 v[96:99], v[128:131], v[184:187], v[96:99]
	v_mfma_f32_16x16x32_bf16 v[88:91], v[148:151], v[180:183], 0
	v_mfma_f32_16x16x32_bf16 v[88:91], v[152:155], v[184:187], v[88:91]
	v_mfma_f32_16x16x32_bf16 v[92:95], v[140:143], v[180:183], 0
	v_mfma_f32_16x16x32_bf16 v[92:95], v[144:147], v[184:187], v[92:95]
	v_mfma_f32_16x16x32_bf16 v[84:87], v[156:159], v[180:183], 0
	v_mfma_f32_16x16x32_bf16 v[84:87], v[160:163], v[184:187], v[84:87]
	v_mfma_f32_16x16x32_bf16 v[80:83], v[124:127], v[196:199], 0
	v_mfma_f32_16x16x32_bf16 v[80:83], v[128:131], v[200:203], v[80:83]
	v_mfma_f32_16x16x32_bf16 v[72:75], v[148:151], v[196:199], 0
	v_mfma_f32_16x16x32_bf16 v[72:75], v[152:155], v[200:203], v[72:75]
	v_mfma_f32_16x16x32_bf16 v[76:79], v[140:143], v[196:199], 0
	v_mfma_f32_16x16x32_bf16 v[76:79], v[144:147], v[200:203], v[76:79]
	v_mfma_f32_16x16x32_bf16 v[68:71], v[156:159], v[196:199], 0
	v_mfma_f32_16x16x32_bf16 v[68:71], v[160:163], v[200:203], v[68:71]
	s_setprio 0
	s_barrier
	s_sleep 2
	s_add_i32 s16, s49, s2
	v_lshl_add_u64 v[204:205], s[20:21], 0, v[2:3]
	s_mov_b32 m0, s16
	ds_read_b128 v[164:167], v221 offset:16384
	ds_read_b128 v[168:171], v221 offset:17408
	ds_read_b128 v[172:175], v221 offset:18432
	ds_read_b128 v[176:179], v221 offset:19456
	ds_read_b128 v[180:183], v221 offset:20480
	ds_read_b128 v[184:187], v221 offset:21504
	ds_read_b128 v[196:199], v221 offset:22528
	ds_read_b128 v[200:203], v221 offset:23552
	global_load_lds_dwordx4 v[204:205], off
	s_add_i32 m0, s16, 0x2000
	s_add_u32 s16, s20, 0x160000
	v_lshl_add_u64 v[206:207], s[20:21], 0, v[190:191]
	s_addc_u32 s17, s21, 0
	s_add_i32 s49, s50, s2
	global_load_lds_dwordx4 v[206:207], off
	v_lshl_add_u64 v[208:209], s[16:17], 0, v[2:3]
	s_mov_b32 m0, s49
	v_lshl_add_u64 v[210:211], s[22:23], 0, v[188:189]
	global_load_lds_dwordx4 v[208:209], off
	v_lshl_add_u64 v[208:209], s[16:17], 0, v[190:191]
	s_add_i32 m0, s49, 0x2000
	s_nop 0
	global_load_lds_dwordx4 v[208:209], off
	v_lshl_add_u64 v[208:209], s[22:23], 0, v[0:1]
	s_mov_b32 m0, s28
	s_nop 0
	global_load_lds_dwordx4 v[208:209], off
	s_mov_b32 m0, s29
	s_nop 0
	global_load_lds_dwordx4 v[210:211], off
	s_waitcnt vmcnt(8)
	s_waitcnt lgkmcnt(0)
	s_barrier
	s_setprio 1
	s_waitcnt lgkmcnt(0)
	v_mfma_f32_16x16x32_bf16 v[64:67], v[124:127], v[164:167], 0
	v_mfma_f32_16x16x32_bf16 v[64:67], v[128:131], v[168:171], v[64:67]
	v_mfma_f32_16x16x32_bf16 v[56:59], v[148:151], v[164:167], 0
	v_mfma_f32_16x16x32_bf16 v[56:59], v[152:155], v[168:171], v[56:59]
	v_mfma_f32_16x16x32_bf16 v[60:63], v[140:143], v[164:167], 0
	v_mfma_f32_16x16x32_bf16 v[60:63], v[144:147], v[168:171], v[60:63]
	v_mfma_f32_16x16x32_bf16 v[52:55], v[156:159], v[164:167], 0
	v_mfma_f32_16x16x32_bf16 v[52:55], v[160:163], v[168:171], v[52:55]
	v_mfma_f32_16x16x32_bf16 v[48:51], v[124:127], v[172:175], 0
	v_mfma_f32_16x16x32_bf16 v[48:51], v[128:131], v[176:179], v[48:51]
	v_mfma_f32_16x16x32_bf16 v[40:43], v[148:151], v[172:175], 0
	v_mfma_f32_16x16x32_bf16 v[40:43], v[152:155], v[176:179], v[40:43]
	v_mfma_f32_16x16x32_bf16 v[44:47], v[140:143], v[172:175], 0
	v_mfma_f32_16x16x32_bf16 v[44:47], v[144:147], v[176:179], v[44:47]
	v_mfma_f32_16x16x32_bf16 v[36:39], v[156:159], v[172:175], 0
	v_mfma_f32_16x16x32_bf16 v[36:39], v[160:163], v[176:179], v[36:39]
	v_mfma_f32_16x16x32_bf16 v[32:35], v[124:127], v[180:183], 0
	v_mfma_f32_16x16x32_bf16 v[32:35], v[128:131], v[184:187], v[32:35]
	v_mfma_f32_16x16x32_bf16 v[24:27], v[148:151], v[180:183], 0
	v_mfma_f32_16x16x32_bf16 v[24:27], v[152:155], v[184:187], v[24:27]
	v_mfma_f32_16x16x32_bf16 v[28:31], v[140:143], v[180:183], 0
	v_mfma_f32_16x16x32_bf16 v[28:31], v[144:147], v[184:187], v[28:31]
	v_mfma_f32_16x16x32_bf16 v[20:23], v[156:159], v[180:183], 0
	v_mfma_f32_16x16x32_bf16 v[20:23], v[160:163], v[184:187], v[20:23]
	v_mfma_f32_16x16x32_bf16 v[16:19], v[124:127], v[196:199], 0
	v_mfma_f32_16x16x32_bf16 v[16:19], v[128:131], v[200:203], v[16:19]
	v_mfma_f32_16x16x32_bf16 v[8:11], v[148:151], v[196:199], 0
	v_mfma_f32_16x16x32_bf16 v[8:11], v[152:155], v[200:203], v[8:11]
	v_mfma_f32_16x16x32_bf16 v[12:15], v[140:143], v[196:199], 0
	v_mfma_f32_16x16x32_bf16 v[12:15], v[144:147], v[200:203], v[12:15]
	v_mfma_f32_16x16x32_bf16 v[4:7], v[156:159], v[196:199], 0
	v_mfma_f32_16x16x32_bf16 v[4:7], v[160:163], v[200:203], v[4:7]
	s_setprio 0
	s_barrier
	s_sleep 1
	s_add_i32 s49, 0, 0x18000
	s_add_i32 s50, 0, 0x1c000
	s_add_u32 s16, s22, 0x160000
	s_addc_u32 s17, s23, 0
	s_mov_b32 m0, s30
	v_lshl_add_u64 v[212:213], s[16:17], 0, v[0:1]
	global_load_lds_dwordx4 v[212:213], off
	v_lshl_add_u64 v[212:213], s[16:17], 0, v[188:189]
	s_mov_b32 m0, s31
	s_nop 0
	global_load_lds_dwordx4 v[212:213], off
	v_add_u32_e32 v144, s49, v219
	v_add_u32_e32 v160, s50, v219
	ds_read_b128 v[124:127], v144
	ds_read_b128 v[128:131], v144 offset:1024
	ds_read_b128 v[140:143], v144 offset:2048
	ds_read_b128 v[144:147], v144 offset:3072
	ds_read_b128 v[148:151], v160
	ds_read_b128 v[152:155], v160 offset:1024
	ds_read_b128 v[156:159], v160 offset:2048
	ds_read_b128 v[160:163], v160 offset:3072
	ds_read_b128 v[164:167], v221 offset:32768
	ds_read_b128 v[168:171], v221 offset:33792
	ds_read_b128 v[172:175], v221 offset:34816
	ds_read_b128 v[176:179], v221 offset:35840
	ds_read_b128 v[180:183], v221 offset:36864
	ds_read_b128 v[184:187], v221 offset:37888
	ds_read_b128 v[196:199], v221 offset:38912
	ds_read_b128 v[200:203], v221 offset:39936
	s_waitcnt vmcnt(8)
	s_waitcnt lgkmcnt(0)
	s_barrier
	s_setprio 1
	s_waitcnt lgkmcnt(0)
	v_mfma_f32_16x16x32_bf16 v[136:139], v[124:127], v[164:167], v[136:139]
	v_mfma_f32_16x16x32_bf16 v[136:139], v[128:131], v[168:171], v[136:139]
	v_mfma_f32_16x16x32_bf16 v[120:123], v[148:151], v[164:167], v[120:123]
	v_mfma_f32_16x16x32_bf16 v[120:123], v[152:155], v[168:171], v[120:123]
	v_mfma_f32_16x16x32_bf16 v[132:135], v[140:143], v[164:167], v[132:135]
	v_mfma_f32_16x16x32_bf16 v[132:135], v[144:147], v[168:171], v[132:135]
	v_mfma_f32_16x16x32_bf16 v[116:119], v[156:159], v[164:167], v[116:119]
	v_mfma_f32_16x16x32_bf16 v[116:119], v[160:163], v[168:171], v[116:119]
	v_mfma_f32_16x16x32_bf16 v[112:115], v[124:127], v[172:175], v[112:115]
	v_mfma_f32_16x16x32_bf16 v[112:115], v[128:131], v[176:179], v[112:115]
	v_mfma_f32_16x16x32_bf16 v[104:107], v[148:151], v[172:175], v[104:107]
	v_mfma_f32_16x16x32_bf16 v[104:107], v[152:155], v[176:179], v[104:107]
	v_mfma_f32_16x16x32_bf16 v[108:111], v[140:143], v[172:175], v[108:111]
	v_mfma_f32_16x16x32_bf16 v[108:111], v[144:147], v[176:179], v[108:111]
	v_mfma_f32_16x16x32_bf16 v[100:103], v[156:159], v[172:175], v[100:103]
	v_mfma_f32_16x16x32_bf16 v[100:103], v[160:163], v[176:179], v[100:103]
	v_mfma_f32_16x16x32_bf16 v[96:99], v[124:127], v[180:183], v[96:99]
	v_mfma_f32_16x16x32_bf16 v[96:99], v[128:131], v[184:187], v[96:99]
	v_mfma_f32_16x16x32_bf16 v[88:91], v[148:151], v[180:183], v[88:91]
	v_mfma_f32_16x16x32_bf16 v[88:91], v[152:155], v[184:187], v[88:91]
	v_mfma_f32_16x16x32_bf16 v[92:95], v[140:143], v[180:183], v[92:95]
	v_mfma_f32_16x16x32_bf16 v[92:95], v[144:147], v[184:187], v[92:95]
	v_mfma_f32_16x16x32_bf16 v[84:87], v[156:159], v[180:183], v[84:87]
	v_mfma_f32_16x16x32_bf16 v[84:87], v[160:163], v[184:187], v[84:87]
	v_mfma_f32_16x16x32_bf16 v[80:83], v[124:127], v[196:199], v[80:83]
	v_mfma_f32_16x16x32_bf16 v[80:83], v[128:131], v[200:203], v[80:83]
	v_mfma_f32_16x16x32_bf16 v[72:75], v[148:151], v[196:199], v[72:75]
	v_mfma_f32_16x16x32_bf16 v[72:75], v[152:155], v[200:203], v[72:75]
	v_mfma_f32_16x16x32_bf16 v[76:79], v[140:143], v[196:199], v[76:79]
	v_mfma_f32_16x16x32_bf16 v[76:79], v[144:147], v[200:203], v[76:79]
	v_mfma_f32_16x16x32_bf16 v[68:71], v[156:159], v[196:199], v[68:71]
	v_mfma_f32_16x16x32_bf16 v[68:71], v[160:163], v[200:203], v[68:71]
	s_setprio 0
	s_barrier
	s_sleep 2
	s_add_i32 s16, s49, s2
	v_lshl_add_u64 v[204:205], v[204:205], 0, s[66:67]
	s_mov_b32 m0, s16
	ds_read_b128 v[164:167], v221 offset:49152
	ds_read_b128 v[168:171], v221 offset:50176
	ds_read_b128 v[172:175], v221 offset:51200
	ds_read_b128 v[176:179], v221 offset:52224
	ds_read_b128 v[180:183], v221 offset:53248
	ds_read_b128 v[184:187], v221 offset:54272
	ds_read_b128 v[196:199], v221 offset:55296
	ds_read_b128 v[200:203], v221 offset:56320
	global_load_lds_dwordx4 v[204:205], off
	s_add_i32 m0, s16, 0x2000
	s_add_u32 s16, s20, 0x160080
	v_lshl_add_u64 v[204:205], v[206:207], 0, s[66:67]
	s_addc_u32 s17, s21, 0
	s_add_i32 s20, s50, s2
	global_load_lds_dwordx4 v[204:205], off
	v_lshl_add_u64 v[204:205], s[16:17], 0, v[2:3]
	s_mov_b32 m0, s20
	s_nop 0
	global_load_lds_dwordx4 v[204:205], off
	v_lshl_add_u64 v[204:205], s[16:17], 0, v[190:191]
	s_add_i32 m0, s20, 0x2000
	s_nop 0
	global_load_lds_dwordx4 v[204:205], off
	v_lshl_add_u64 v[204:205], v[208:209], 0, s[66:67]
	s_mov_b32 m0, s34
	s_nop 0
	global_load_lds_dwordx4 v[204:205], off
	v_lshl_add_u64 v[204:205], v[210:211], 0, s[66:67]
	s_mov_b32 m0, s35
	s_nop 0
	global_load_lds_dwordx4 v[204:205], off
	s_waitcnt vmcnt(8)
	s_waitcnt lgkmcnt(0)
	s_barrier
	s_setprio 1
	s_waitcnt lgkmcnt(0)
	v_mfma_f32_16x16x32_bf16 v[64:67], v[124:127], v[164:167], v[64:67]
	v_mfma_f32_16x16x32_bf16 v[64:67], v[128:131], v[168:171], v[64:67]
	v_mfma_f32_16x16x32_bf16 v[56:59], v[148:151], v[164:167], v[56:59]
	v_mfma_f32_16x16x32_bf16 v[56:59], v[152:155], v[168:171], v[56:59]
	v_mfma_f32_16x16x32_bf16 v[60:63], v[140:143], v[164:167], v[60:63]
	v_mfma_f32_16x16x32_bf16 v[60:63], v[144:147], v[168:171], v[60:63]
	v_mfma_f32_16x16x32_bf16 v[52:55], v[156:159], v[164:167], v[52:55]
	v_mfma_f32_16x16x32_bf16 v[52:55], v[160:163], v[168:171], v[52:55]
	v_mfma_f32_16x16x32_bf16 v[48:51], v[124:127], v[172:175], v[48:51]
	v_mfma_f32_16x16x32_bf16 v[48:51], v[128:131], v[176:179], v[48:51]
	v_mfma_f32_16x16x32_bf16 v[40:43], v[148:151], v[172:175], v[40:43]
	v_mfma_f32_16x16x32_bf16 v[40:43], v[152:155], v[176:179], v[40:43]
	v_mfma_f32_16x16x32_bf16 v[44:47], v[140:143], v[172:175], v[44:47]
	v_mfma_f32_16x16x32_bf16 v[44:47], v[144:147], v[176:179], v[44:47]
	v_mfma_f32_16x16x32_bf16 v[36:39], v[156:159], v[172:175], v[36:39]
	v_mfma_f32_16x16x32_bf16 v[36:39], v[160:163], v[176:179], v[36:39]
	v_mfma_f32_16x16x32_bf16 v[32:35], v[124:127], v[180:183], v[32:35]
	v_mfma_f32_16x16x32_bf16 v[32:35], v[128:131], v[184:187], v[32:35]
	v_mfma_f32_16x16x32_bf16 v[24:27], v[148:151], v[180:183], v[24:27]
	v_mfma_f32_16x16x32_bf16 v[24:27], v[152:155], v[184:187], v[24:27]
	v_mfma_f32_16x16x32_bf16 v[28:31], v[140:143], v[180:183], v[28:31]
	v_mfma_f32_16x16x32_bf16 v[28:31], v[144:147], v[184:187], v[28:31]
	v_mfma_f32_16x16x32_bf16 v[20:23], v[156:159], v[180:183], v[20:23]
	v_mfma_f32_16x16x32_bf16 v[20:23], v[160:163], v[184:187], v[20:23]
	v_mfma_f32_16x16x32_bf16 v[16:19], v[124:127], v[196:199], v[16:19]
	v_mfma_f32_16x16x32_bf16 v[16:19], v[128:131], v[200:203], v[16:19]
	v_mfma_f32_16x16x32_bf16 v[8:11], v[148:151], v[196:199], v[8:11]
	v_mfma_f32_16x16x32_bf16 v[8:11], v[152:155], v[200:203], v[8:11]
	v_mfma_f32_16x16x32_bf16 v[12:15], v[140:143], v[196:199], v[12:15]
	v_mfma_f32_16x16x32_bf16 v[12:15], v[144:147], v[200:203], v[12:15]
	v_mfma_f32_16x16x32_bf16 v[4:7], v[156:159], v[196:199], v[4:7]
	v_mfma_f32_16x16x32_bf16 v[4:7], v[160:163], v[200:203], v[4:7]
	s_setprio 0
	s_barrier
	s_add_i32 s48, s48, 2
	s_add_u32 s40, s40, 0x100
	s_addc_u32 s41, s41, 0
	s_cmpk_gt_u32 s48, 0x55
	s_mov_b64 s[16:17], s[18:19]

.LBB0_346:
	s_add_u32 s38, s16, 0x100
	s_addc_u32 s39, s17, 0
	s_mov_b32 s43, -2
	s_add_u32 s16, s14, 0x100
	s_addc_u32 s17, s15, 0
	s_add_i32 s44, 0, 0x10000
	s_cmpk_eq_i32 s43, 0x54
	s_cselect_b32 s21, s11, s17
	s_cselect_b32 s20, s10, s16
	s_cselect_b32 s19, s13, s39
	s_cselect_b32 s18, s12, s38
	s_add_i32 s45, 0, 0x14000
	v_add_u32_e32 v144, s44, v236
	v_add_u32_e32 v160, s45, v236
	ds_read_b128 v[132:135], v144
	ds_read_b128 v[136:139], v144 offset:1024
	ds_read_b128 v[140:143], v144 offset:2048
	ds_read_b128 v[144:147], v144 offset:3072
	ds_read_b128 v[148:151], v160
	ds_read_b128 v[152:155], v160 offset:1024
	ds_read_b128 v[156:159], v160 offset:2048
	ds_read_b128 v[160:163], v160 offset:3072
	ds_read_b128 v[164:167], v238
	ds_read_b128 v[168:171], v238 offset:1024
	ds_read_b128 v[172:175], v238 offset:2048
	ds_read_b128 v[176:179], v238 offset:3072
	ds_read_b128 v[180:183], v238 offset:4096
	ds_read_b128 v[184:187], v238 offset:5120
	ds_read_b128 v[188:191], v238 offset:6144
	ds_read_b128 v[192:195], v238 offset:7168
	v_lshl_add_u64 v[204:205], s[14:15], 0, v[200:201]
	s_add_i32 m0, s23, 0xc000
	s_nop 0
	global_load_lds_dwordx4 v[204:205], off
	v_lshl_add_u64 v[204:205], s[14:15], 0, v[202:203]
	s_add_i32 m0, s23, 0xe000
	s_nop 0
	global_load_lds_dwordx4 v[204:205], off
	s_waitcnt vmcnt(8)
	s_waitcnt lgkmcnt(0)
	s_barrier
	s_setprio 1
	s_waitcnt lgkmcnt(0)
	v_mfma_f32_16x16x32_bf16 v[128:131], v[132:135], v[164:167], 0
	v_mfma_f32_16x16x32_bf16 v[128:131], v[136:139], v[168:171], v[128:131]
	v_mfma_f32_16x16x32_bf16 v[120:123], v[148:151], v[164:167], 0
	v_mfma_f32_16x16x32_bf16 v[120:123], v[152:155], v[168:171], v[120:123]
	v_mfma_f32_16x16x32_bf16 v[124:127], v[140:143], v[164:167], 0
	v_mfma_f32_16x16x32_bf16 v[124:127], v[144:147], v[168:171], v[124:127]
	v_mfma_f32_16x16x32_bf16 v[112:115], v[156:159], v[164:167], 0
	v_mfma_f32_16x16x32_bf16 v[112:115], v[160:163], v[168:171], v[112:115]
	v_mfma_f32_16x16x32_bf16 v[116:119], v[132:135], v[172:175], 0
	v_mfma_f32_16x16x32_bf16 v[116:119], v[136:139], v[176:179], v[116:119]
	v_mfma_f32_16x16x32_bf16 v[104:107], v[148:151], v[172:175], 0
	v_mfma_f32_16x16x32_bf16 v[104:107], v[152:155], v[176:179], v[104:107]
	v_mfma_f32_16x16x32_bf16 v[108:111], v[140:143], v[172:175], 0
	v_mfma_f32_16x16x32_bf16 v[108:111], v[144:147], v[176:179], v[108:111]
	v_mfma_f32_16x16x32_bf16 v[96:99], v[156:159], v[172:175], 0
	v_mfma_f32_16x16x32_bf16 v[96:99], v[160:163], v[176:179], v[96:99]
	v_mfma_f32_16x16x32_bf16 v[100:103], v[132:135], v[180:183], 0
	v_mfma_f32_16x16x32_bf16 v[100:103], v[136:139], v[184:187], v[100:103]
	v_mfma_f32_16x16x32_bf16 v[88:91], v[148:151], v[180:183], 0
	v_mfma_f32_16x16x32_bf16 v[88:91], v[152:155], v[184:187], v[88:91]
	v_mfma_f32_16x16x32_bf16 v[92:95], v[140:143], v[180:183], 0
	v_mfma_f32_16x16x32_bf16 v[92:95], v[144:147], v[184:187], v[92:95]
	v_mfma_f32_16x16x32_bf16 v[80:83], v[156:159], v[180:183], 0
	v_mfma_f32_16x16x32_bf16 v[80:83], v[160:163], v[184:187], v[80:83]
	v_mfma_f32_16x16x32_bf16 v[84:87], v[132:135], v[188:191], 0
	v_mfma_f32_16x16x32_bf16 v[84:87], v[136:139], v[192:195], v[84:87]
	v_mfma_f32_16x16x32_bf16 v[72:75], v[148:151], v[188:191], 0
	v_mfma_f32_16x16x32_bf16 v[72:75], v[152:155], v[192:195], v[72:75]
	v_mfma_f32_16x16x32_bf16 v[76:79], v[140:143], v[188:191], 0
	v_mfma_f32_16x16x32_bf16 v[76:79], v[144:147], v[192:195], v[76:79]
	v_mfma_f32_16x16x32_bf16 v[68:71], v[156:159], v[188:191], 0
	v_mfma_f32_16x16x32_bf16 v[68:71], v[160:163], v[192:195], v[68:71]
	s_setprio 0
	s_barrier
	s_sleep 2
	s_add_i32 s14, s44, s22
	v_lshl_add_u64 v[204:205], s[18:19], 0, v[2:3]
	s_mov_b32 m0, s14
	ds_read_b128 v[164:167], v238 offset:16384
	ds_read_b128 v[168:171], v238 offset:17408
	ds_read_b128 v[172:175], v238 offset:18432
	ds_read_b128 v[176:179], v238 offset:19456
	ds_read_b128 v[180:183], v238 offset:20480
	ds_read_b128 v[184:187], v238 offset:21504
	ds_read_b128 v[188:191], v238 offset:22528
	ds_read_b128 v[192:195], v238 offset:23552
	global_load_lds_dwordx4 v[204:205], off
	s_add_i32 m0, s14, 0x2000
	s_add_u32 s14, s18, 0x160000
	v_lshl_add_u64 v[206:207], s[18:19], 0, v[198:199]
	s_addc_u32 s15, s19, 0
	s_add_i32 s44, s45, s22
	global_load_lds_dwordx4 v[206:207], off
	v_lshl_add_u64 v[208:209], s[14:15], 0, v[2:3]
	s_mov_b32 m0, s44
	v_lshl_add_u64 v[210:211], s[20:21], 0, v[196:197]
	global_load_lds_dwordx4 v[208:209], off
	v_lshl_add_u64 v[208:209], s[14:15], 0, v[198:199]
	s_add_i32 m0, s44, 0x2000
	s_nop 0
	global_load_lds_dwordx4 v[208:209], off
	v_lshl_add_u64 v[208:209], s[20:21], 0, v[0:1]
	s_mov_b32 m0, s23
	s_nop 0
	global_load_lds_dwordx4 v[208:209], off
	s_mov_b32 m0, s28
	s_nop 0
	global_load_lds_dwordx4 v[210:211], off
	s_waitcnt vmcnt(8)
	s_waitcnt lgkmcnt(0)
	s_barrier
	s_setprio 1
	s_waitcnt lgkmcnt(0)
	v_mfma_f32_16x16x32_bf16 v[64:67], v[132:135], v[164:167], 0
	v_mfma_f32_16x16x32_bf16 v[64:67], v[136:139], v[168:171], v[64:67]
	v_mfma_f32_16x16x32_bf16 v[56:59], v[148:151], v[164:167], 0
	v_mfma_f32_16x16x32_bf16 v[56:59], v[152:155], v[168:171], v[56:59]
	v_mfma_f32_16x16x32_bf16 v[60:63], v[140:143], v[164:167], 0
	v_mfma_f32_16x16x32_bf16 v[60:63], v[144:147], v[168:171], v[60:63]
	v_mfma_f32_16x16x32_bf16 v[48:51], v[156:159], v[164:167], 0
	v_mfma_f32_16x16x32_bf16 v[48:51], v[160:163], v[168:171], v[48:51]
	v_mfma_f32_16x16x32_bf16 v[52:55], v[132:135], v[172:175], 0
	v_mfma_f32_16x16x32_bf16 v[52:55], v[136:139], v[176:179], v[52:55]
	v_mfma_f32_16x16x32_bf16 v[40:43], v[148:151], v[172:175], 0
	v_mfma_f32_16x16x32_bf16 v[40:43], v[152:155], v[176:179], v[40:43]
	v_mfma_f32_16x16x32_bf16 v[44:47], v[140:143], v[172:175], 0
	v_mfma_f32_16x16x32_bf16 v[44:47], v[144:147], v[176:179], v[44:47]
	v_mfma_f32_16x16x32_bf16 v[32:35], v[156:159], v[172:175], 0
	v_mfma_f32_16x16x32_bf16 v[32:35], v[160:163], v[176:179], v[32:35]
	v_mfma_f32_16x16x32_bf16 v[36:39], v[132:135], v[180:183], 0
	v_mfma_f32_16x16x32_bf16 v[36:39], v[136:139], v[184:187], v[36:39]
	v_mfma_f32_16x16x32_bf16 v[24:27], v[148:151], v[180:183], 0
	v_mfma_f32_16x16x32_bf16 v[24:27], v[152:155], v[184:187], v[24:27]
	v_mfma_f32_16x16x32_bf16 v[28:31], v[140:143], v[180:183], 0
	v_mfma_f32_16x16x32_bf16 v[28:31], v[144:147], v[184:187], v[28:31]
	v_mfma_f32_16x16x32_bf16 v[16:19], v[156:159], v[180:183], 0
	v_mfma_f32_16x16x32_bf16 v[16:19], v[160:163], v[184:187], v[16:19]
	v_mfma_f32_16x16x32_bf16 v[20:23], v[132:135], v[188:191], 0
	v_mfma_f32_16x16x32_bf16 v[20:23], v[136:139], v[192:195], v[20:23]
	v_mfma_f32_16x16x32_bf16 v[8:11], v[148:151], v[188:191], 0
	v_mfma_f32_16x16x32_bf16 v[8:11], v[152:155], v[192:195], v[8:11]
	v_mfma_f32_16x16x32_bf16 v[12:15], v[140:143], v[188:191], 0
	v_mfma_f32_16x16x32_bf16 v[12:15], v[144:147], v[192:195], v[12:15]
	v_mfma_f32_16x16x32_bf16 v[4:7], v[156:159], v[188:191], 0
	v_mfma_f32_16x16x32_bf16 v[4:7], v[160:163], v[192:195], v[4:7]
	s_setprio 0
	s_barrier
	s_sleep 1
	s_add_i32 s44, 0, 0x18000
	s_add_i32 s45, 0, 0x1c000
	s_add_u32 s14, s20, 0x160000
	s_addc_u32 s15, s21, 0
	s_mov_b32 m0, s29
	v_lshl_add_u64 v[212:213], s[14:15], 0, v[0:1]
	global_load_lds_dwordx4 v[212:213], off
	v_lshl_add_u64 v[212:213], s[14:15], 0, v[196:197]
	s_mov_b32 m0, s30
	s_nop 0
	global_load_lds_dwordx4 v[212:213], off
	v_add_u32_e32 v144, s44, v236
	v_add_u32_e32 v160, s45, v236
	ds_read_b128 v[132:135], v144
	ds_read_b128 v[136:139], v144 offset:1024
	ds_read_b128 v[140:143], v144 offset:2048
	ds_read_b128 v[144:147], v144 offset:3072
	ds_read_b128 v[148:151], v160
	ds_read_b128 v[152:155], v160 offset:1024
	ds_read_b128 v[156:159], v160 offset:2048
	ds_read_b128 v[160:163], v160 offset:3072
	ds_read_b128 v[164:167], v238 offset:32768
	ds_read_b128 v[168:171], v238 offset:33792
	ds_read_b128 v[172:175], v238 offset:34816
	ds_read_b128 v[176:179], v238 offset:35840
	ds_read_b128 v[180:183], v238 offset:36864
	ds_read_b128 v[184:187], v238 offset:37888
	ds_read_b128 v[188:191], v238 offset:38912
	ds_read_b128 v[192:195], v238 offset:39936
	s_waitcnt vmcnt(8)
	s_waitcnt lgkmcnt(0)
	s_barrier
	s_setprio 1
	s_waitcnt lgkmcnt(0)
	v_mfma_f32_16x16x32_bf16 v[128:131], v[132:135], v[164:167], v[128:131]
	v_mfma_f32_16x16x32_bf16 v[128:131], v[136:139], v[168:171], v[128:131]
	v_mfma_f32_16x16x32_bf16 v[120:123], v[148:151], v[164:167], v[120:123]
	v_mfma_f32_16x16x32_bf16 v[120:123], v[152:155], v[168:171], v[120:123]
	v_mfma_f32_16x16x32_bf16 v[124:127], v[140:143], v[164:167], v[124:127]
	v_mfma_f32_16x16x32_bf16 v[124:127], v[144:147], v[168:171], v[124:127]
	v_mfma_f32_16x16x32_bf16 v[112:115], v[156:159], v[164:167], v[112:115]
	v_mfma_f32_16x16x32_bf16 v[112:115], v[160:163], v[168:171], v[112:115]
	v_mfma_f32_16x16x32_bf16 v[116:119], v[132:135], v[172:175], v[116:119]
	v_mfma_f32_16x16x32_bf16 v[116:119], v[136:139], v[176:179], v[116:119]
	v_mfma_f32_16x16x32_bf16 v[104:107], v[148:151], v[172:175], v[104:107]
	v_mfma_f32_16x16x32_bf16 v[104:107], v[152:155], v[176:179], v[104:107]
	v_mfma_f32_16x16x32_bf16 v[108:111], v[140:143], v[172:175], v[108:111]
	v_mfma_f32_16x16x32_bf16 v[108:111], v[144:147], v[176:179], v[108:111]
	v_mfma_f32_16x16x32_bf16 v[96:99], v[156:159], v[172:175], v[96:99]
	v_mfma_f32_16x16x32_bf16 v[96:99], v[160:163], v[176:179], v[96:99]
	v_mfma_f32_16x16x32_bf16 v[100:103], v[132:135], v[180:183], v[100:103]
	v_mfma_f32_16x16x32_bf16 v[100:103], v[136:139], v[184:187], v[100:103]
	v_mfma_f32_16x16x32_bf16 v[88:91], v[148:151], v[180:183], v[88:91]
	v_mfma_f32_16x16x32_bf16 v[88:91], v[152:155], v[184:187], v[88:91]
	v_mfma_f32_16x16x32_bf16 v[92:95], v[140:143], v[180:183], v[92:95]
	v_mfma_f32_16x16x32_bf16 v[92:95], v[144:147], v[184:187], v[92:95]
	v_mfma_f32_16x16x32_bf16 v[80:83], v[156:159], v[180:183], v[80:83]
	v_mfma_f32_16x16x32_bf16 v[80:83], v[160:163], v[184:187], v[80:83]
	v_mfma_f32_16x16x32_bf16 v[84:87], v[132:135], v[188:191], v[84:87]
	v_mfma_f32_16x16x32_bf16 v[84:87], v[136:139], v[192:195], v[84:87]
	v_mfma_f32_16x16x32_bf16 v[72:75], v[148:151], v[188:191], v[72:75]
	v_mfma_f32_16x16x32_bf16 v[72:75], v[152:155], v[192:195], v[72:75]
	v_mfma_f32_16x16x32_bf16 v[76:79], v[140:143], v[188:191], v[76:79]
	v_mfma_f32_16x16x32_bf16 v[76:79], v[144:147], v[192:195], v[76:79]
	v_mfma_f32_16x16x32_bf16 v[68:71], v[156:159], v[188:191], v[68:71]
	v_mfma_f32_16x16x32_bf16 v[68:71], v[160:163], v[192:195], v[68:71]
	s_setprio 0
	s_barrier
	s_sleep 2
	s_add_i32 s14, s44, s22
	v_lshl_add_u64 v[204:205], v[204:205], 0, s[66:67]
	s_mov_b32 m0, s14
	ds_read_b128 v[164:167], v238 offset:49152
	ds_read_b128 v[168:171], v238 offset:50176
	ds_read_b128 v[172:175], v238 offset:51200
	ds_read_b128 v[176:179], v238 offset:52224
	ds_read_b128 v[180:183], v238 offset:53248
	ds_read_b128 v[184:187], v238 offset:54272
	ds_read_b128 v[188:191], v238 offset:55296
	ds_read_b128 v[192:195], v238 offset:56320
	global_load_lds_dwordx4 v[204:205], off
	s_add_i32 m0, s14, 0x2000
	s_add_u32 s14, s18, 0x160080
	v_lshl_add_u64 v[204:205], v[206:207], 0, s[66:67]
	s_addc_u32 s15, s19, 0
	s_add_i32 s18, s45, s22
	global_load_lds_dwordx4 v[204:205], off
	v_lshl_add_u64 v[204:205], s[14:15], 0, v[2:3]
	s_mov_b32 m0, s18
	s_nop 0
	global_load_lds_dwordx4 v[204:205], off
	v_lshl_add_u64 v[204:205], s[14:15], 0, v[198:199]
	s_add_i32 m0, s18, 0x2000
	s_nop 0
	global_load_lds_dwordx4 v[204:205], off
	v_lshl_add_u64 v[204:205], v[208:209], 0, s[66:67]
	s_mov_b32 m0, s31
	s_nop 0
	global_load_lds_dwordx4 v[204:205], off
	v_lshl_add_u64 v[204:205], v[210:211], 0, s[66:67]
	s_mov_b32 m0, s34
	s_nop 0
	global_load_lds_dwordx4 v[204:205], off
	s_waitcnt vmcnt(8)
	s_waitcnt lgkmcnt(0)
	s_barrier
	s_setprio 1
	s_waitcnt lgkmcnt(0)
	v_mfma_f32_16x16x32_bf16 v[64:67], v[132:135], v[164:167], v[64:67]
	v_mfma_f32_16x16x32_bf16 v[64:67], v[136:139], v[168:171], v[64:67]
	v_mfma_f32_16x16x32_bf16 v[56:59], v[148:151], v[164:167], v[56:59]
	v_mfma_f32_16x16x32_bf16 v[56:59], v[152:155], v[168:171], v[56:59]
	v_mfma_f32_16x16x32_bf16 v[60:63], v[140:143], v[164:167], v[60:63]
	v_mfma_f32_16x16x32_bf16 v[60:63], v[144:147], v[168:171], v[60:63]
	v_mfma_f32_16x16x32_bf16 v[48:51], v[156:159], v[164:167], v[48:51]
	v_mfma_f32_16x16x32_bf16 v[48:51], v[160:163], v[168:171], v[48:51]
	v_mfma_f32_16x16x32_bf16 v[52:55], v[132:135], v[172:175], v[52:55]
	v_mfma_f32_16x16x32_bf16 v[52:55], v[136:139], v[176:179], v[52:55]
	v_mfma_f32_16x16x32_bf16 v[40:43], v[148:151], v[172:175], v[40:43]
	v_mfma_f32_16x16x32_bf16 v[40:43], v[152:155], v[176:179], v[40:43]
	v_mfma_f32_16x16x32_bf16 v[44:47], v[140:143], v[172:175], v[44:47]
	v_mfma_f32_16x16x32_bf16 v[44:47], v[144:147], v[176:179], v[44:47]
	v_mfma_f32_16x16x32_bf16 v[32:35], v[156:159], v[172:175], v[32:35]
	v_mfma_f32_16x16x32_bf16 v[32:35], v[160:163], v[176:179], v[32:35]
	v_mfma_f32_16x16x32_bf16 v[36:39], v[132:135], v[180:183], v[36:39]
	v_mfma_f32_16x16x32_bf16 v[36:39], v[136:139], v[184:187], v[36:39]
	v_mfma_f32_16x16x32_bf16 v[24:27], v[148:151], v[180:183], v[24:27]
	v_mfma_f32_16x16x32_bf16 v[24:27], v[152:155], v[184:187], v[24:27]
	v_mfma_f32_16x16x32_bf16 v[28:31], v[140:143], v[180:183], v[28:31]
	v_mfma_f32_16x16x32_bf16 v[28:31], v[144:147], v[184:187], v[28:31]
	v_mfma_f32_16x16x32_bf16 v[16:19], v[156:159], v[180:183], v[16:19]
	v_mfma_f32_16x16x32_bf16 v[16:19], v[160:163], v[184:187], v[16:19]
	v_mfma_f32_16x16x32_bf16 v[20:23], v[132:135], v[188:191], v[20:23]
	v_mfma_f32_16x16x32_bf16 v[20:23], v[136:139], v[192:195], v[20:23]
	v_mfma_f32_16x16x32_bf16 v[8:11], v[148:151], v[188:191], v[8:11]
	v_mfma_f32_16x16x32_bf16 v[8:11], v[152:155], v[192:195], v[8:11]
	v_mfma_f32_16x16x32_bf16 v[12:15], v[140:143], v[188:191], v[12:15]
	v_mfma_f32_16x16x32_bf16 v[12:15], v[144:147], v[192:195], v[12:15]
	v_mfma_f32_16x16x32_bf16 v[4:7], v[156:159], v[188:191], v[4:7]
	v_mfma_f32_16x16x32_bf16 v[4:7], v[160:163], v[192:195], v[4:7]
	s_setprio 0
	s_barrier
	s_add_i32 s43, s43, 2
	s_add_u32 s38, s38, 0x100
	s_addc_u32 s39, s39, 0
	s_cmpk_gt_u32 s43, 0x55
	s_mov_b64 s[14:15], s[16:17]

.LBB0_429:
	s_ashr_i32 s23, s22, 31
	s_lshl_b64 s[24:25], s[22:23], 20
	s_add_u32 s24, s51, s24
	s_addc_u32 s25, s52, s25
	s_and_b64 s[26:27], s[40:41], exec
	s_cselect_b32 s5, s25, s29
	s_cselect_b32 s23, s24, s28
	s_ashr_i32 s21, s20, 31
	s_lshl_b64 s[26:27], s[20:21], 20
	s_add_u32 s26, s12, s26
	s_addc_u32 s27, s13, s27
	s_and_b64 s[42:43], s[40:41], exec
	s_cselect_b32 s21, s27, s31
	s_cselect_b32 s62, s26, s30
	s_add_u32 s28, s28, 0x80080
	s_addc_u32 s29, s29, 0
	s_add_u32 s63, s30, 0x100
	s_addc_u32 s68, s31, 0
	s_mov_b32 s69, -2
	s_add_u32 s30, s28, 0xfff80080
	s_addc_u32 s31, s29, -1
	s_add_i32 s70, 0, 0x10000
	s_cmp_eq_u32 s69, 28
	s_cselect_b32 s43, s5, s31
	s_cselect_b32 s42, s23, s30
	s_cselect_b32 s31, s21, s68
	s_cselect_b32 s30, s62, s63
	s_add_i32 s73, 0, 0x14000
	s_waitcnt lgkmcnt(0)
	v_add_u32_e32 v152, s70, v163
	v_add_u32_e32 v160, s73, v163
	ds_read_b128 v[132:135], v152
	ds_read_b128 v[136:139], v152 offset:1024
	ds_read_b128 v[148:151], v152 offset:2048
	ds_read_b128 v[152:155], v152 offset:3072
	ds_read_b128 v[156:159], v160
	ds_read_b128 v[170:173], v160 offset:1024
	ds_read_b128 v[174:177], v160 offset:2048
	ds_read_b128 v[178:181], v160 offset:3072
	ds_read_b128 v[182:185], v167
	ds_read_b128 v[186:189], v167 offset:1024
	ds_read_b128 v[190:193], v167 offset:2048
	ds_read_b128 v[194:197], v167 offset:3072
	ds_read_b128 v[198:201], v167 offset:4096
	ds_read_b128 v[208:211], v167 offset:5120
	ds_read_b128 v[212:215], v167 offset:6144
	ds_read_b128 v[216:219], v167 offset:7168
	v_lshl_add_u64 v[160:161], s[28:29], 0, v[144:145]
	s_add_i32 m0, s15, 0xc000
	s_nop 0
	global_load_lds_dwordx4 v[160:161], off
	v_lshl_add_u64 v[160:161], s[28:29], 0, v[146:147]
	s_add_i32 m0, s15, 0xe000
	s_nop 0
	global_load_lds_dwordx4 v[160:161], off
	s_waitcnt vmcnt(8)
	s_waitcnt lgkmcnt(0)
	s_barrier
	s_setprio 1
	s_waitcnt lgkmcnt(0)
	v_mfma_f32_16x16x32_bf16 v[128:131], v[132:135], v[182:185], 0
	v_mfma_f32_16x16x32_bf16 v[128:131], v[136:139], v[186:189], v[128:131]
	v_mfma_f32_16x16x32_bf16 v[116:119], v[156:159], v[182:185], 0
	v_mfma_f32_16x16x32_bf16 v[116:119], v[170:173], v[186:189], v[116:119]
	v_mfma_f32_16x16x32_bf16 v[124:127], v[148:151], v[182:185], 0
	v_mfma_f32_16x16x32_bf16 v[124:127], v[152:155], v[186:189], v[124:127]
	v_mfma_f32_16x16x32_bf16 v[108:111], v[174:177], v[182:185], 0
	v_mfma_f32_16x16x32_bf16 v[108:111], v[178:181], v[186:189], v[108:111]
	v_mfma_f32_16x16x32_bf16 v[120:123], v[132:135], v[190:193], 0
	v_mfma_f32_16x16x32_bf16 v[120:123], v[136:139], v[194:197], v[120:123]
	v_mfma_f32_16x16x32_bf16 v[100:103], v[156:159], v[190:193], 0
	v_mfma_f32_16x16x32_bf16 v[100:103], v[170:173], v[194:197], v[100:103]
	v_mfma_f32_16x16x32_bf16 v[112:115], v[148:151], v[190:193], 0
	v_mfma_f32_16x16x32_bf16 v[112:115], v[152:155], v[194:197], v[112:115]
	v_mfma_f32_16x16x32_bf16 v[92:95], v[174:177], v[190:193], 0
	v_mfma_f32_16x16x32_bf16 v[92:95], v[178:181], v[194:197], v[92:95]
	v_mfma_f32_16x16x32_bf16 v[104:107], v[132:135], v[198:201], 0
	v_mfma_f32_16x16x32_bf16 v[104:107], v[136:139], v[208:211], v[104:107]
	v_mfma_f32_16x16x32_bf16 v[84:87], v[156:159], v[198:201], 0
	v_mfma_f32_16x16x32_bf16 v[84:87], v[170:173], v[208:211], v[84:87]
	v_mfma_f32_16x16x32_bf16 v[96:99], v[148:151], v[198:201], 0
	v_mfma_f32_16x16x32_bf16 v[96:99], v[152:155], v[208:211], v[96:99]
	v_mfma_f32_16x16x32_bf16 v[76:79], v[174:177], v[198:201], 0
	v_mfma_f32_16x16x32_bf16 v[76:79], v[178:181], v[208:211], v[76:79]
	v_mfma_f32_16x16x32_bf16 v[88:91], v[132:135], v[212:215], 0
	v_mfma_f32_16x16x32_bf16 v[88:91], v[136:139], v[216:219], v[88:91]
	v_mfma_f32_16x16x32_bf16 v[72:75], v[156:159], v[212:215], 0
	v_mfma_f32_16x16x32_bf16 v[72:75], v[170:173], v[216:219], v[72:75]
	v_mfma_f32_16x16x32_bf16 v[80:83], v[148:151], v[212:215], 0
	v_mfma_f32_16x16x32_bf16 v[80:83], v[152:155], v[216:219], v[80:83]
	v_mfma_f32_16x16x32_bf16 v[68:71], v[174:177], v[212:215], 0
	v_mfma_f32_16x16x32_bf16 v[68:71], v[178:181], v[216:219], v[68:71]
	s_setprio 0
	s_barrier
	s_sleep 2
	s_add_i32 s70, s70, s0
	v_lshl_add_u64 v[160:161], s[30:31], 0, v[2:3]
	s_mov_b32 m0, s70
	ds_read_b128 v[182:185], v167 offset:16384
	ds_read_b128 v[186:189], v167 offset:17408
	ds_read_b128 v[190:193], v167 offset:18432
	ds_read_b128 v[194:197], v167 offset:19456
	ds_read_b128 v[198:201], v167 offset:20480
	ds_read_b128 v[208:211], v167 offset:21504
	ds_read_b128 v[212:215], v167 offset:22528
	ds_read_b128 v[216:219], v167 offset:23552
	global_load_lds_dwordx4 v[160:161], off
	s_add_i32 m0, s70, 0x2000
	s_add_u32 s70, s30, 0x80000
	v_lshl_add_u64 v[202:203], s[30:31], 0, v[142:143]
	s_addc_u32 s71, s31, 0
	s_add_i32 s73, s73, s0
	global_load_lds_dwordx4 v[202:203], off
	v_lshl_add_u64 v[204:205], s[70:71], 0, v[2:3]
	s_mov_b32 m0, s73
	v_lshl_add_u64 v[206:207], s[42:43], 0, v[140:141]
	global_load_lds_dwordx4 v[204:205], off
	v_lshl_add_u64 v[204:205], s[70:71], 0, v[142:143]
	s_add_i32 m0, s73, 0x2000
	s_nop 0
	global_load_lds_dwordx4 v[204:205], off
	v_lshl_add_u64 v[204:205], s[42:43], 0, v[0:1]
	s_mov_b32 m0, s15
	s_nop 0
	global_load_lds_dwordx4 v[204:205], off
	s_mov_b32 m0, s53
	s_nop 0
	global_load_lds_dwordx4 v[206:207], off
	s_waitcnt vmcnt(8)
	s_waitcnt lgkmcnt(0)
	s_barrier
	s_setprio 1
	s_waitcnt lgkmcnt(0)
	v_mfma_f32_16x16x32_bf16 v[64:67], v[132:135], v[182:185], 0
	v_mfma_f32_16x16x32_bf16 v[64:67], v[136:139], v[186:189], v[64:67]
	v_mfma_f32_16x16x32_bf16 v[52:55], v[156:159], v[182:185], 0
	v_mfma_f32_16x16x32_bf16 v[52:55], v[170:173], v[186:189], v[52:55]
	v_mfma_f32_16x16x32_bf16 v[60:63], v[148:151], v[182:185], 0
	v_mfma_f32_16x16x32_bf16 v[60:63], v[152:155], v[186:189], v[60:63]
	v_mfma_f32_16x16x32_bf16 v[44:47], v[174:177], v[182:185], 0
	v_mfma_f32_16x16x32_bf16 v[44:47], v[178:181], v[186:189], v[44:47]
	v_mfma_f32_16x16x32_bf16 v[56:59], v[132:135], v[190:193], 0
	v_mfma_f32_16x16x32_bf16 v[56:59], v[136:139], v[194:197], v[56:59]
	v_mfma_f32_16x16x32_bf16 v[36:39], v[156:159], v[190:193], 0
	v_mfma_f32_16x16x32_bf16 v[36:39], v[170:173], v[194:197], v[36:39]
	v_mfma_f32_16x16x32_bf16 v[48:51], v[148:151], v[190:193], 0
	v_mfma_f32_16x16x32_bf16 v[48:51], v[152:155], v[194:197], v[48:51]
	v_mfma_f32_16x16x32_bf16 v[28:31], v[174:177], v[190:193], 0
	v_mfma_f32_16x16x32_bf16 v[28:31], v[178:181], v[194:197], v[28:31]
	v_mfma_f32_16x16x32_bf16 v[40:43], v[132:135], v[198:201], 0
	v_mfma_f32_16x16x32_bf16 v[40:43], v[136:139], v[208:211], v[40:43]
	v_mfma_f32_16x16x32_bf16 v[20:23], v[156:159], v[198:201], 0
	v_mfma_f32_16x16x32_bf16 v[20:23], v[170:173], v[208:211], v[20:23]
	v_mfma_f32_16x16x32_bf16 v[32:35], v[148:151], v[198:201], 0
	v_mfma_f32_16x16x32_bf16 v[32:35], v[152:155], v[208:211], v[32:35]
	v_mfma_f32_16x16x32_bf16 v[12:15], v[174:177], v[198:201], 0
	v_mfma_f32_16x16x32_bf16 v[12:15], v[178:181], v[208:211], v[12:15]
	v_mfma_f32_16x16x32_bf16 v[24:27], v[132:135], v[212:215], 0
	v_mfma_f32_16x16x32_bf16 v[24:27], v[136:139], v[216:219], v[24:27]
	v_mfma_f32_16x16x32_bf16 v[8:11], v[156:159], v[212:215], 0
	v_mfma_f32_16x16x32_bf16 v[8:11], v[170:173], v[216:219], v[8:11]
	v_mfma_f32_16x16x32_bf16 v[16:19], v[148:151], v[212:215], 0
	v_mfma_f32_16x16x32_bf16 v[16:19], v[152:155], v[216:219], v[16:19]
	v_mfma_f32_16x16x32_bf16 v[4:7], v[174:177], v[212:215], 0
	v_mfma_f32_16x16x32_bf16 v[4:7], v[178:181], v[216:219], v[4:7]
	s_setprio 0
	s_barrier
	s_sleep 1
	s_add_i32 s70, 0, 0x18000
	s_add_i32 s71, 0, 0x1c000
	s_add_u32 s42, s42, 0x80000
	s_addc_u32 s43, s43, 0
	s_mov_b32 m0, s54
	v_lshl_add_u64 v[220:221], s[42:43], 0, v[0:1]
	global_load_lds_dwordx4 v[220:221], off
	v_lshl_add_u64 v[220:221], s[42:43], 0, v[140:141]
	s_mov_b32 m0, s55
	s_nop 0
	global_load_lds_dwordx4 v[220:221], off
	v_add_u32_e32 v152, s70, v163
	v_add_u32_e32 v178, s71, v163
	ds_read_b128 v[132:135], v152
	ds_read_b128 v[136:139], v152 offset:1024
	ds_read_b128 v[148:151], v152 offset:2048
	ds_read_b128 v[152:155], v152 offset:3072
	ds_read_b128 v[156:159], v178
	ds_read_b128 v[170:173], v178 offset:1024
	ds_read_b128 v[174:177], v178 offset:2048
	ds_read_b128 v[178:181], v178 offset:3072
	ds_read_b128 v[182:185], v167 offset:32768
	ds_read_b128 v[186:189], v167 offset:33792
	ds_read_b128 v[190:193], v167 offset:34816
	ds_read_b128 v[194:197], v167 offset:35840
	ds_read_b128 v[198:201], v167 offset:36864
	ds_read_b128 v[208:211], v167 offset:37888
	ds_read_b128 v[212:215], v167 offset:38912
	ds_read_b128 v[216:219], v167 offset:39936
	s_waitcnt vmcnt(8)
	s_waitcnt lgkmcnt(0)
	s_barrier
	s_setprio 1
	s_waitcnt lgkmcnt(0)
	v_mfma_f32_16x16x32_bf16 v[128:131], v[132:135], v[182:185], v[128:131]
	v_mfma_f32_16x16x32_bf16 v[128:131], v[136:139], v[186:189], v[128:131]
	v_mfma_f32_16x16x32_bf16 v[116:119], v[156:159], v[182:185], v[116:119]
	v_mfma_f32_16x16x32_bf16 v[116:119], v[170:173], v[186:189], v[116:119]
	v_mfma_f32_16x16x32_bf16 v[124:127], v[148:151], v[182:185], v[124:127]
	v_mfma_f32_16x16x32_bf16 v[124:127], v[152:155], v[186:189], v[124:127]
	v_mfma_f32_16x16x32_bf16 v[108:111], v[174:177], v[182:185], v[108:111]
	v_mfma_f32_16x16x32_bf16 v[108:111], v[178:181], v[186:189], v[108:111]
	v_mfma_f32_16x16x32_bf16 v[120:123], v[132:135], v[190:193], v[120:123]
	v_mfma_f32_16x16x32_bf16 v[120:123], v[136:139], v[194:197], v[120:123]
	v_mfma_f32_16x16x32_bf16 v[100:103], v[156:159], v[190:193], v[100:103]
	v_mfma_f32_16x16x32_bf16 v[100:103], v[170:173], v[194:197], v[100:103]
	v_mfma_f32_16x16x32_bf16 v[112:115], v[148:151], v[190:193], v[112:115]
	v_mfma_f32_16x16x32_bf16 v[112:115], v[152:155], v[194:197], v[112:115]
	v_mfma_f32_16x16x32_bf16 v[92:95], v[174:177], v[190:193], v[92:95]
	v_mfma_f32_16x16x32_bf16 v[92:95], v[178:181], v[194:197], v[92:95]
	v_mfma_f32_16x16x32_bf16 v[104:107], v[132:135], v[198:201], v[104:107]
	v_mfma_f32_16x16x32_bf16 v[104:107], v[136:139], v[208:211], v[104:107]
	v_mfma_f32_16x16x32_bf16 v[84:87], v[156:159], v[198:201], v[84:87]
	v_mfma_f32_16x16x32_bf16 v[84:87], v[170:173], v[208:211], v[84:87]
	v_mfma_f32_16x16x32_bf16 v[96:99], v[148:151], v[198:201], v[96:99]
	v_mfma_f32_16x16x32_bf16 v[96:99], v[152:155], v[208:211], v[96:99]
	v_mfma_f32_16x16x32_bf16 v[76:79], v[174:177], v[198:201], v[76:79]
	v_mfma_f32_16x16x32_bf16 v[76:79], v[178:181], v[208:211], v[76:79]
	v_mfma_f32_16x16x32_bf16 v[88:91], v[132:135], v[212:215], v[88:91]
	v_mfma_f32_16x16x32_bf16 v[88:91], v[136:139], v[216:219], v[88:91]
	v_mfma_f32_16x16x32_bf16 v[72:75], v[156:159], v[212:215], v[72:75]
	v_mfma_f32_16x16x32_bf16 v[72:75], v[170:173], v[216:219], v[72:75]
	v_mfma_f32_16x16x32_bf16 v[80:83], v[148:151], v[212:215], v[80:83]
	v_mfma_f32_16x16x32_bf16 v[80:83], v[152:155], v[216:219], v[80:83]
	v_mfma_f32_16x16x32_bf16 v[68:71], v[174:177], v[212:215], v[68:71]
	v_mfma_f32_16x16x32_bf16 v[68:71], v[178:181], v[216:219], v[68:71]
	s_setprio 0
	s_barrier
	s_sleep 2
	s_add_i32 s42, s70, s0
	v_lshl_add_u64 v[160:161], v[160:161], 0, s[66:67]
	s_mov_b32 m0, s42
	ds_read_b128 v[182:185], v167 offset:49152
	ds_read_b128 v[186:189], v167 offset:50176
	ds_read_b128 v[190:193], v167 offset:51200
	ds_read_b128 v[194:197], v167 offset:52224
	ds_read_b128 v[198:201], v167 offset:53248
	ds_read_b128 v[208:211], v167 offset:54272
	ds_read_b128 v[212:215], v167 offset:55296
	ds_read_b128 v[216:219], v167 offset:56320
	global_load_lds_dwordx4 v[160:161], off
	s_add_i32 m0, s42, 0x2000
	s_add_u32 s30, s30, 0x80080
	v_lshl_add_u64 v[160:161], v[202:203], 0, s[66:67]
	s_addc_u32 s31, s31, 0
	s_add_i32 s42, s71, s0
	global_load_lds_dwordx4 v[160:161], off
	v_lshl_add_u64 v[160:161], s[30:31], 0, v[2:3]
	s_mov_b32 m0, s42
	s_nop 0
	global_load_lds_dwordx4 v[160:161], off
	v_lshl_add_u64 v[160:161], s[30:31], 0, v[142:143]
	s_add_i32 m0, s42, 0x2000
	s_nop 0
	global_load_lds_dwordx4 v[160:161], off
	v_lshl_add_u64 v[160:161], v[204:205], 0, s[66:67]
	s_mov_b32 m0, s60
	s_nop 0
	global_load_lds_dwordx4 v[160:161], off
	v_lshl_add_u64 v[160:161], v[206:207], 0, s[66:67]
	s_mov_b32 m0, s64
	s_nop 0
	global_load_lds_dwordx4 v[160:161], off
	s_waitcnt vmcnt(8)
	s_waitcnt lgkmcnt(0)
	s_barrier
	s_setprio 1
	s_waitcnt lgkmcnt(0)
	v_mfma_f32_16x16x32_bf16 v[64:67], v[132:135], v[182:185], v[64:67]
	v_mfma_f32_16x16x32_bf16 v[64:67], v[136:139], v[186:189], v[64:67]
	v_mfma_f32_16x16x32_bf16 v[52:55], v[156:159], v[182:185], v[52:55]
	v_mfma_f32_16x16x32_bf16 v[52:55], v[170:173], v[186:189], v[52:55]
	v_mfma_f32_16x16x32_bf16 v[60:63], v[148:151], v[182:185], v[60:63]
	v_mfma_f32_16x16x32_bf16 v[60:63], v[152:155], v[186:189], v[60:63]
	v_mfma_f32_16x16x32_bf16 v[44:47], v[174:177], v[182:185], v[44:47]
	v_mfma_f32_16x16x32_bf16 v[44:47], v[178:181], v[186:189], v[44:47]
	v_mfma_f32_16x16x32_bf16 v[56:59], v[132:135], v[190:193], v[56:59]
	v_mfma_f32_16x16x32_bf16 v[56:59], v[136:139], v[194:197], v[56:59]
	v_mfma_f32_16x16x32_bf16 v[36:39], v[156:159], v[190:193], v[36:39]
	v_mfma_f32_16x16x32_bf16 v[36:39], v[170:173], v[194:197], v[36:39]
	v_mfma_f32_16x16x32_bf16 v[48:51], v[148:151], v[190:193], v[48:51]
	v_mfma_f32_16x16x32_bf16 v[48:51], v[152:155], v[194:197], v[48:51]
	v_mfma_f32_16x16x32_bf16 v[28:31], v[174:177], v[190:193], v[28:31]
	v_mfma_f32_16x16x32_bf16 v[28:31], v[178:181], v[194:197], v[28:31]
	v_mfma_f32_16x16x32_bf16 v[40:43], v[132:135], v[198:201], v[40:43]
	v_mfma_f32_16x16x32_bf16 v[40:43], v[136:139], v[208:211], v[40:43]
	v_mfma_f32_16x16x32_bf16 v[20:23], v[156:159], v[198:201], v[20:23]
	v_mfma_f32_16x16x32_bf16 v[20:23], v[170:173], v[208:211], v[20:23]
	v_mfma_f32_16x16x32_bf16 v[32:35], v[148:151], v[198:201], v[32:35]
	v_mfma_f32_16x16x32_bf16 v[32:35], v[152:155], v[208:211], v[32:35]
	v_mfma_f32_16x16x32_bf16 v[12:15], v[174:177], v[198:201], v[12:15]
	v_mfma_f32_16x16x32_bf16 v[12:15], v[178:181], v[208:211], v[12:15]
	v_mfma_f32_16x16x32_bf16 v[24:27], v[132:135], v[212:215], v[24:27]
	v_mfma_f32_16x16x32_bf16 v[24:27], v[136:139], v[216:219], v[24:27]
	v_mfma_f32_16x16x32_bf16 v[8:11], v[156:159], v[212:215], v[8:11]
	v_mfma_f32_16x16x32_bf16 v[8:11], v[170:173], v[216:219], v[8:11]
	v_mfma_f32_16x16x32_bf16 v[16:19], v[148:151], v[212:215], v[16:19]
	v_mfma_f32_16x16x32_bf16 v[16:19], v[152:155], v[216:219], v[16:19]
	v_mfma_f32_16x16x32_bf16 v[4:7], v[174:177], v[212:215], v[4:7]
	v_mfma_f32_16x16x32_bf16 v[4:7], v[178:181], v[216:219], v[4:7]
	s_setprio 0
	s_barrier
	s_add_i32 s69, s69, 2
	s_add_u32 s28, s28, 0x100
	s_addc_u32 s29, s29, 0
	s_add_u32 s63, s63, 0x100
	s_addc_u32 s68, s68, 0
	s_cmp_gt_u32 s69, 29

.LBB0_494:
	s_ashr_i32 s15, s14, 31
	s_lshl_b64 s[16:17], s[14:15], 20
	s_add_u32 s16, s27, s16
	s_addc_u32 s17, s28, s17
	s_and_b64 s[18:19], s[38:39], exec
	s_cselect_b32 s15, s17, s21
	s_cselect_b32 s43, s16, s20
	s_ashr_i32 s11, s10, 31
	s_lshl_b64 s[18:19], s[10:11], 20
	s_add_u32 s18, s29, s18
	s_addc_u32 s19, s30, s19
	s_and_b64 s[24:25], s[38:39], exec
	s_cselect_b32 s11, s19, s23
	s_cselect_b32 s44, s18, s22
	s_add_u32 s20, s20, 0x80080
	s_addc_u32 s21, s21, 0
	s_add_u32 s45, s22, 0x100
	s_addc_u32 s46, s23, 0
	s_mov_b32 s47, -2
	s_add_u32 s22, s20, 0xfff80080
	s_addc_u32 s23, s21, -1
	s_add_i32 s48, 0, 0x10000
	s_cmp_eq_u32 s47, 28
	s_cselect_b32 s25, s15, s23
	s_cselect_b32 s24, s43, s22
	s_cselect_b32 s23, s11, s46
	s_cselect_b32 s22, s44, s45
	s_add_i32 s50, 0, 0x14000
	s_waitcnt lgkmcnt(0)
	v_add_u32_e32 v152, s48, v137
	v_add_u32_e32 v168, s50, v137
	ds_read_b128 v[140:143], v152
	ds_read_b128 v[144:147], v152 offset:1024
	ds_read_b128 v[148:151], v152 offset:2048
	ds_read_b128 v[152:155], v152 offset:3072
	ds_read_b128 v[156:159], v168
	ds_read_b128 v[160:163], v168 offset:1024
	ds_read_b128 v[164:167], v168 offset:2048
	ds_read_b128 v[168:171], v168 offset:3072
	ds_read_b128 v[172:175], v139
	ds_read_b128 v[176:179], v139 offset:1024
	ds_read_b128 v[180:183], v139 offset:2048
	ds_read_b128 v[184:187], v139 offset:3072
	ds_read_b128 v[188:191], v139 offset:4096
	ds_read_b128 v[192:195], v139 offset:5120
	ds_read_b128 v[196:199], v139 offset:6144
	ds_read_b128 v[200:203], v139 offset:7168
	v_lshl_add_u64 v[204:205], s[20:21], 0, v[132:133]
	s_add_i32 m0, s31, 0xc000
	s_nop 0
	global_load_lds_dwordx4 v[204:205], off
	v_lshl_add_u64 v[204:205], s[20:21], 0, v[134:135]
	s_add_i32 m0, s31, 0xe000
	s_nop 0
	global_load_lds_dwordx4 v[204:205], off
	s_waitcnt vmcnt(8)
	s_waitcnt lgkmcnt(0)
	s_barrier
	s_setprio 1
	s_waitcnt lgkmcnt(0)
	v_mfma_f32_16x16x32_bf16 v[128:131], v[140:143], v[172:175], 0
	v_mfma_f32_16x16x32_bf16 v[128:131], v[144:147], v[176:179], v[128:131]
	v_mfma_f32_16x16x32_bf16 v[112:115], v[156:159], v[172:175], 0
	v_mfma_f32_16x16x32_bf16 v[112:115], v[160:163], v[176:179], v[112:115]
	v_mfma_f32_16x16x32_bf16 v[124:127], v[148:151], v[172:175], 0
	v_mfma_f32_16x16x32_bf16 v[124:127], v[152:155], v[176:179], v[124:127]
	v_mfma_f32_16x16x32_bf16 v[104:107], v[164:167], v[172:175], 0
	v_mfma_f32_16x16x32_bf16 v[104:107], v[168:171], v[176:179], v[104:107]
	v_mfma_f32_16x16x32_bf16 v[120:123], v[140:143], v[180:183], 0
	v_mfma_f32_16x16x32_bf16 v[120:123], v[144:147], v[184:187], v[120:123]
	v_mfma_f32_16x16x32_bf16 v[96:99], v[156:159], v[180:183], 0
	v_mfma_f32_16x16x32_bf16 v[96:99], v[160:163], v[184:187], v[96:99]
	v_mfma_f32_16x16x32_bf16 v[116:119], v[148:151], v[180:183], 0
	v_mfma_f32_16x16x32_bf16 v[116:119], v[152:155], v[184:187], v[116:119]
	v_mfma_f32_16x16x32_bf16 v[88:91], v[164:167], v[180:183], 0
	v_mfma_f32_16x16x32_bf16 v[88:91], v[168:171], v[184:187], v[88:91]
	v_mfma_f32_16x16x32_bf16 v[108:111], v[140:143], v[188:191], 0
	v_mfma_f32_16x16x32_bf16 v[108:111], v[144:147], v[192:195], v[108:111]
	v_mfma_f32_16x16x32_bf16 v[80:83], v[156:159], v[188:191], 0
	v_mfma_f32_16x16x32_bf16 v[80:83], v[160:163], v[192:195], v[80:83]
	v_mfma_f32_16x16x32_bf16 v[100:103], v[148:151], v[188:191], 0
	v_mfma_f32_16x16x32_bf16 v[100:103], v[152:155], v[192:195], v[100:103]
	v_mfma_f32_16x16x32_bf16 v[76:79], v[164:167], v[188:191], 0
	v_mfma_f32_16x16x32_bf16 v[76:79], v[168:171], v[192:195], v[76:79]
	v_mfma_f32_16x16x32_bf16 v[92:95], v[140:143], v[196:199], 0
	v_mfma_f32_16x16x32_bf16 v[92:95], v[144:147], v[200:203], v[92:95]
	v_mfma_f32_16x16x32_bf16 v[72:75], v[156:159], v[196:199], 0
	v_mfma_f32_16x16x32_bf16 v[72:75], v[160:163], v[200:203], v[72:75]
	v_mfma_f32_16x16x32_bf16 v[84:87], v[148:151], v[196:199], 0
	v_mfma_f32_16x16x32_bf16 v[84:87], v[152:155], v[200:203], v[84:87]
	v_mfma_f32_16x16x32_bf16 v[68:71], v[164:167], v[196:199], 0
	v_mfma_f32_16x16x32_bf16 v[68:71], v[168:171], v[200:203], v[68:71]
	s_setprio 0
	s_barrier
	s_sleep 2
	s_add_i32 s48, s48, s0
	v_lshl_add_u64 v[204:205], s[22:23], 0, v[2:3]
	s_mov_b32 m0, s48
	ds_read_b128 v[172:175], v139 offset:16384
	ds_read_b128 v[176:179], v139 offset:17408
	ds_read_b128 v[180:183], v139 offset:18432
	ds_read_b128 v[184:187], v139 offset:19456
	ds_read_b128 v[188:191], v139 offset:20480
	ds_read_b128 v[192:195], v139 offset:21504
	ds_read_b128 v[196:199], v139 offset:22528
	ds_read_b128 v[200:203], v139 offset:23552
	global_load_lds_dwordx4 v[204:205], off
	s_add_i32 m0, s48, 0x2000
	s_add_u32 s48, s22, 0x80000
	v_lshl_add_u64 v[206:207], s[22:23], 0, v[0:1]
	s_addc_u32 s49, s23, 0
	s_add_i32 s50, s50, s0
	global_load_lds_dwordx4 v[206:207], off
	v_lshl_add_u64 v[208:209], s[48:49], 0, v[2:3]
	s_mov_b32 m0, s50
	v_lshl_add_u64 v[210:211], s[24:25], 0, v[0:1]
	global_load_lds_dwordx4 v[208:209], off
	v_lshl_add_u64 v[208:209], s[48:49], 0, v[0:1]
	s_add_i32 m0, s50, 0x2000
	s_nop 0
	global_load_lds_dwordx4 v[208:209], off
	v_lshl_add_u64 v[208:209], s[24:25], 0, v[2:3]
	s_mov_b32 m0, s31
	s_nop 0
	global_load_lds_dwordx4 v[208:209], off
	s_mov_b32 m0, s40
	s_nop 0
	global_load_lds_dwordx4 v[210:211], off
	s_waitcnt vmcnt(8)
	s_waitcnt lgkmcnt(0)
	s_barrier
	s_setprio 1
	s_waitcnt lgkmcnt(0)
	v_mfma_f32_16x16x32_bf16 v[64:67], v[140:143], v[172:175], 0
	v_mfma_f32_16x16x32_bf16 v[64:67], v[144:147], v[176:179], v[64:67]
	v_mfma_f32_16x16x32_bf16 v[48:51], v[156:159], v[172:175], 0
	v_mfma_f32_16x16x32_bf16 v[48:51], v[160:163], v[176:179], v[48:51]
	v_mfma_f32_16x16x32_bf16 v[60:63], v[148:151], v[172:175], 0
	v_mfma_f32_16x16x32_bf16 v[60:63], v[152:155], v[176:179], v[60:63]
	v_mfma_f32_16x16x32_bf16 v[44:47], v[164:167], v[172:175], 0
	v_mfma_f32_16x16x32_bf16 v[44:47], v[168:171], v[176:179], v[44:47]
	v_mfma_f32_16x16x32_bf16 v[56:59], v[140:143], v[180:183], 0
	v_mfma_f32_16x16x32_bf16 v[56:59], v[144:147], v[184:187], v[56:59]
	v_mfma_f32_16x16x32_bf16 v[32:35], v[156:159], v[180:183], 0
	v_mfma_f32_16x16x32_bf16 v[32:35], v[160:163], v[184:187], v[32:35]
	v_mfma_f32_16x16x32_bf16 v[52:55], v[148:151], v[180:183], 0
	v_mfma_f32_16x16x32_bf16 v[52:55], v[152:155], v[184:187], v[52:55]
	v_mfma_f32_16x16x32_bf16 v[28:31], v[164:167], v[180:183], 0
	v_mfma_f32_16x16x32_bf16 v[28:31], v[168:171], v[184:187], v[28:31]
	v_mfma_f32_16x16x32_bf16 v[40:43], v[140:143], v[188:191], 0
	v_mfma_f32_16x16x32_bf16 v[40:43], v[144:147], v[192:195], v[40:43]
	v_mfma_f32_16x16x32_bf16 v[16:19], v[156:159], v[188:191], 0
	v_mfma_f32_16x16x32_bf16 v[16:19], v[160:163], v[192:195], v[16:19]
	v_mfma_f32_16x16x32_bf16 v[36:39], v[148:151], v[188:191], 0
	v_mfma_f32_16x16x32_bf16 v[36:39], v[152:155], v[192:195], v[36:39]
	v_mfma_f32_16x16x32_bf16 v[12:15], v[164:167], v[188:191], 0
	v_mfma_f32_16x16x32_bf16 v[12:15], v[168:171], v[192:195], v[12:15]
	v_mfma_f32_16x16x32_bf16 v[24:27], v[140:143], v[196:199], 0
	v_mfma_f32_16x16x32_bf16 v[24:27], v[144:147], v[200:203], v[24:27]
	v_mfma_f32_16x16x32_bf16 v[8:11], v[156:159], v[196:199], 0
	v_mfma_f32_16x16x32_bf16 v[8:11], v[160:163], v[200:203], v[8:11]
	v_mfma_f32_16x16x32_bf16 v[20:23], v[148:151], v[196:199], 0
	v_mfma_f32_16x16x32_bf16 v[20:23], v[152:155], v[200:203], v[20:23]
	v_mfma_f32_16x16x32_bf16 v[4:7], v[164:167], v[196:199], 0
	v_mfma_f32_16x16x32_bf16 v[4:7], v[168:171], v[200:203], v[4:7]
	s_setprio 0
	s_barrier
	s_sleep 1
	s_add_i32 s48, 0, 0x18000
	s_add_i32 s49, 0, 0x1c000
	s_add_u32 s24, s24, 0x80000
	s_addc_u32 s25, s25, 0
	s_mov_b32 m0, s41
	v_lshl_add_u64 v[212:213], s[24:25], 0, v[2:3]
	global_load_lds_dwordx4 v[212:213], off
	v_lshl_add_u64 v[212:213], s[24:25], 0, v[0:1]
	s_mov_b32 m0, s42
	s_nop 0
	global_load_lds_dwordx4 v[212:213], off
	v_add_u32_e32 v152, s48, v137
	v_add_u32_e32 v168, s49, v137
	ds_read_b128 v[140:143], v152
	ds_read_b128 v[144:147], v152 offset:1024
	ds_read_b128 v[148:151], v152 offset:2048
	ds_read_b128 v[152:155], v152 offset:3072
	ds_read_b128 v[156:159], v168
	ds_read_b128 v[160:163], v168 offset:1024
	ds_read_b128 v[164:167], v168 offset:2048
	ds_read_b128 v[168:171], v168 offset:3072
	ds_read_b128 v[172:175], v139 offset:32768
	ds_read_b128 v[176:179], v139 offset:33792
	ds_read_b128 v[180:183], v139 offset:34816
	ds_read_b128 v[184:187], v139 offset:35840
	ds_read_b128 v[188:191], v139 offset:36864
	ds_read_b128 v[192:195], v139 offset:37888
	ds_read_b128 v[196:199], v139 offset:38912
	ds_read_b128 v[200:203], v139 offset:39936
	s_waitcnt vmcnt(8)
	s_waitcnt lgkmcnt(0)
	s_barrier
	s_setprio 1
	s_waitcnt lgkmcnt(0)
	v_mfma_f32_16x16x32_bf16 v[128:131], v[140:143], v[172:175], v[128:131]
	v_mfma_f32_16x16x32_bf16 v[128:131], v[144:147], v[176:179], v[128:131]
	v_mfma_f32_16x16x32_bf16 v[112:115], v[156:159], v[172:175], v[112:115]
	v_mfma_f32_16x16x32_bf16 v[112:115], v[160:163], v[176:179], v[112:115]
	v_mfma_f32_16x16x32_bf16 v[124:127], v[148:151], v[172:175], v[124:127]
	v_mfma_f32_16x16x32_bf16 v[124:127], v[152:155], v[176:179], v[124:127]
	v_mfma_f32_16x16x32_bf16 v[104:107], v[164:167], v[172:175], v[104:107]
	v_mfma_f32_16x16x32_bf16 v[104:107], v[168:171], v[176:179], v[104:107]
	v_mfma_f32_16x16x32_bf16 v[120:123], v[140:143], v[180:183], v[120:123]
	v_mfma_f32_16x16x32_bf16 v[120:123], v[144:147], v[184:187], v[120:123]
	v_mfma_f32_16x16x32_bf16 v[96:99], v[156:159], v[180:183], v[96:99]
	v_mfma_f32_16x16x32_bf16 v[96:99], v[160:163], v[184:187], v[96:99]
	v_mfma_f32_16x16x32_bf16 v[116:119], v[148:151], v[180:183], v[116:119]
	v_mfma_f32_16x16x32_bf16 v[116:119], v[152:155], v[184:187], v[116:119]
	v_mfma_f32_16x16x32_bf16 v[88:91], v[164:167], v[180:183], v[88:91]
	v_mfma_f32_16x16x32_bf16 v[88:91], v[168:171], v[184:187], v[88:91]
	v_mfma_f32_16x16x32_bf16 v[108:111], v[140:143], v[188:191], v[108:111]
	v_mfma_f32_16x16x32_bf16 v[108:111], v[144:147], v[192:195], v[108:111]
	v_mfma_f32_16x16x32_bf16 v[80:83], v[156:159], v[188:191], v[80:83]
	v_mfma_f32_16x16x32_bf16 v[80:83], v[160:163], v[192:195], v[80:83]
	v_mfma_f32_16x16x32_bf16 v[100:103], v[148:151], v[188:191], v[100:103]
	v_mfma_f32_16x16x32_bf16 v[100:103], v[152:155], v[192:195], v[100:103]
	v_mfma_f32_16x16x32_bf16 v[76:79], v[164:167], v[188:191], v[76:79]
	v_mfma_f32_16x16x32_bf16 v[76:79], v[168:171], v[192:195], v[76:79]
	v_mfma_f32_16x16x32_bf16 v[92:95], v[140:143], v[196:199], v[92:95]
	v_mfma_f32_16x16x32_bf16 v[92:95], v[144:147], v[200:203], v[92:95]
	v_mfma_f32_16x16x32_bf16 v[72:75], v[156:159], v[196:199], v[72:75]
	v_mfma_f32_16x16x32_bf16 v[72:75], v[160:163], v[200:203], v[72:75]
	v_mfma_f32_16x16x32_bf16 v[84:87], v[148:151], v[196:199], v[84:87]
	v_mfma_f32_16x16x32_bf16 v[84:87], v[152:155], v[200:203], v[84:87]
	v_mfma_f32_16x16x32_bf16 v[68:71], v[164:167], v[196:199], v[68:71]
	v_mfma_f32_16x16x32_bf16 v[68:71], v[168:171], v[200:203], v[68:71]
	s_setprio 0
	s_barrier
	s_sleep 2
	s_add_i32 s24, s48, s0
	v_lshl_add_u64 v[204:205], v[204:205], 0, s[66:67]
	s_mov_b32 m0, s24
	ds_read_b128 v[172:175], v139 offset:49152
	ds_read_b128 v[176:179], v139 offset:50176
	ds_read_b128 v[180:183], v139 offset:51200
	ds_read_b128 v[184:187], v139 offset:52224
	ds_read_b128 v[188:191], v139 offset:53248
	ds_read_b128 v[192:195], v139 offset:54272
	ds_read_b128 v[196:199], v139 offset:55296
	ds_read_b128 v[200:203], v139 offset:56320
	global_load_lds_dwordx4 v[204:205], off
	s_add_i32 m0, s24, 0x2000
	s_add_u32 s22, s22, 0x80080
	v_lshl_add_u64 v[204:205], v[206:207], 0, s[66:67]
	s_addc_u32 s23, s23, 0
	s_add_i32 s24, s49, s0
	global_load_lds_dwordx4 v[204:205], off
	v_lshl_add_u64 v[204:205], s[22:23], 0, v[2:3]
	s_mov_b32 m0, s24
	s_nop 0
	global_load_lds_dwordx4 v[204:205], off
	v_lshl_add_u64 v[204:205], s[22:23], 0, v[0:1]
	s_add_i32 m0, s24, 0x2000
	s_nop 0
	global_load_lds_dwordx4 v[204:205], off
	v_lshl_add_u64 v[204:205], v[208:209], 0, s[66:67]
	s_mov_b32 m0, s1
	s_nop 0
	global_load_lds_dwordx4 v[204:205], off
	v_lshl_add_u64 v[204:205], v[210:211], 0, s[66:67]
	s_mov_b32 m0, s34
	s_nop 0
	global_load_lds_dwordx4 v[204:205], off
	s_waitcnt vmcnt(8)
	s_waitcnt lgkmcnt(0)
	s_barrier
	s_setprio 1
	s_waitcnt lgkmcnt(0)
	v_mfma_f32_16x16x32_bf16 v[64:67], v[140:143], v[172:175], v[64:67]
	v_mfma_f32_16x16x32_bf16 v[64:67], v[144:147], v[176:179], v[64:67]
	v_mfma_f32_16x16x32_bf16 v[48:51], v[156:159], v[172:175], v[48:51]
	v_mfma_f32_16x16x32_bf16 v[48:51], v[160:163], v[176:179], v[48:51]
	v_mfma_f32_16x16x32_bf16 v[60:63], v[148:151], v[172:175], v[60:63]
	v_mfma_f32_16x16x32_bf16 v[60:63], v[152:155], v[176:179], v[60:63]
	v_mfma_f32_16x16x32_bf16 v[44:47], v[164:167], v[172:175], v[44:47]
	v_mfma_f32_16x16x32_bf16 v[44:47], v[168:171], v[176:179], v[44:47]
	v_mfma_f32_16x16x32_bf16 v[56:59], v[140:143], v[180:183], v[56:59]
	v_mfma_f32_16x16x32_bf16 v[56:59], v[144:147], v[184:187], v[56:59]
	v_mfma_f32_16x16x32_bf16 v[32:35], v[156:159], v[180:183], v[32:35]
	v_mfma_f32_16x16x32_bf16 v[32:35], v[160:163], v[184:187], v[32:35]
	v_mfma_f32_16x16x32_bf16 v[52:55], v[148:151], v[180:183], v[52:55]
	v_mfma_f32_16x16x32_bf16 v[52:55], v[152:155], v[184:187], v[52:55]
	v_mfma_f32_16x16x32_bf16 v[28:31], v[164:167], v[180:183], v[28:31]
	v_mfma_f32_16x16x32_bf16 v[28:31], v[168:171], v[184:187], v[28:31]
	v_mfma_f32_16x16x32_bf16 v[40:43], v[140:143], v[188:191], v[40:43]
	v_mfma_f32_16x16x32_bf16 v[40:43], v[144:147], v[192:195], v[40:43]
	v_mfma_f32_16x16x32_bf16 v[16:19], v[156:159], v[188:191], v[16:19]
	v_mfma_f32_16x16x32_bf16 v[16:19], v[160:163], v[192:195], v[16:19]
	v_mfma_f32_16x16x32_bf16 v[36:39], v[148:151], v[188:191], v[36:39]
	v_mfma_f32_16x16x32_bf16 v[36:39], v[152:155], v[192:195], v[36:39]
	v_mfma_f32_16x16x32_bf16 v[12:15], v[164:167], v[188:191], v[12:15]
	v_mfma_f32_16x16x32_bf16 v[12:15], v[168:171], v[192:195], v[12:15]
	v_mfma_f32_16x16x32_bf16 v[24:27], v[140:143], v[196:199], v[24:27]
	v_mfma_f32_16x16x32_bf16 v[24:27], v[144:147], v[200:203], v[24:27]
	v_mfma_f32_16x16x32_bf16 v[8:11], v[156:159], v[196:199], v[8:11]
	v_mfma_f32_16x16x32_bf16 v[8:11], v[160:163], v[200:203], v[8:11]
	v_mfma_f32_16x16x32_bf16 v[20:23], v[148:151], v[196:199], v[20:23]
	v_mfma_f32_16x16x32_bf16 v[20:23], v[152:155], v[200:203], v[20:23]
	v_mfma_f32_16x16x32_bf16 v[4:7], v[164:167], v[196:199], v[4:7]
	v_mfma_f32_16x16x32_bf16 v[4:7], v[168:171], v[200:203], v[4:7]
	s_setprio 0
	s_barrier
	s_add_i32 s47, s47, 2
	s_add_u32 s20, s20, 0x100
	s_addc_u32 s21, s21, 0
	s_add_u32 s45, s45, 0x100
	s_addc_u32 s46, s46, 0
	s_cmp_gt_u32 s47, 29

.LBB0_1009:
	s_ashr_i32 s13, s12, 31
	s_lshl_b64 s[14:15], s[12:13], 20
	s_add_u32 s14, s1, s14
	s_addc_u32 s15, s2, s15
	s_and_b64 s[16:17], s[38:39], exec
	s_cselect_b32 s13, s15, s23
	s_cselect_b32 s19, s14, s22
	s_ashr_i32 s11, s10, 31
	s_lshl_b64 s[16:17], s[10:11], 20
	s_add_u32 s16, s28, s16
	s_addc_u32 s17, s29, s17
	s_and_b64 s[26:27], s[38:39], exec
	s_cselect_b32 s11, s17, s25
	s_cselect_b32 s45, s16, s24
	s_add_u32 s22, s22, 0x80080
	s_addc_u32 s23, s23, 0
	s_add_u32 s46, s24, 0x100
	s_addc_u32 s47, s25, 0
	s_mov_b32 s48, -2
	s_add_u32 s24, s22, 0xfff80080
	s_addc_u32 s25, s23, -1
	s_add_i32 s49, 0, 0x10000
	s_cmp_eq_u32 s48, 28
	s_cselect_b32 s27, s13, s25
	s_cselect_b32 s26, s19, s24
	s_cselect_b32 s25, s11, s47
	s_cselect_b32 s24, s45, s46
	s_add_i32 s52, 0, 0x14000
	v_add_u32_e32 v144, s49, v219
	v_add_u32_e32 v160, s52, v219
	ds_read_b128 v[116:119], v144
	ds_read_b128 v[124:127], v144 offset:1024
	ds_read_b128 v[132:135], v144 offset:2048
	ds_read_b128 v[144:147], v144 offset:3072
	ds_read_b128 v[148:151], v160
	ds_read_b128 v[152:155], v160 offset:1024
	ds_read_b128 v[156:159], v160 offset:2048
	ds_read_b128 v[160:163], v160 offset:3072
	ds_read_b128 v[164:167], v221
	ds_read_b128 v[168:171], v221 offset:1024
	ds_read_b128 v[172:175], v221 offset:2048
	ds_read_b128 v[176:179], v221 offset:3072
	ds_read_b128 v[180:183], v221 offset:4096
	ds_read_b128 v[184:187], v221 offset:5120
	ds_read_b128 v[196:199], v221 offset:6144
	ds_read_b128 v[200:203], v221 offset:7168
	v_lshl_add_u64 v[204:205], s[22:23], 0, v[192:193]
	s_add_i32 m0, s21, 0xc000
	s_nop 0
	global_load_lds_dwordx4 v[204:205], off
	v_lshl_add_u64 v[204:205], s[22:23], 0, v[194:195]
	s_add_i32 m0, s21, 0xe000
	s_nop 0
	global_load_lds_dwordx4 v[204:205], off
	s_waitcnt vmcnt(8)
	s_waitcnt lgkmcnt(0)
	s_barrier
	s_setprio 1
	s_waitcnt lgkmcnt(0)
	v_mfma_f32_16x16x32_bf16 v[140:143], v[116:119], v[164:167], 0
	v_mfma_f32_16x16x32_bf16 v[140:143], v[124:127], v[168:171], v[140:143]
	v_mfma_f32_16x16x32_bf16 v[128:131], v[148:151], v[164:167], 0
	v_mfma_f32_16x16x32_bf16 v[128:131], v[152:155], v[168:171], v[128:131]
	v_mfma_f32_16x16x32_bf16 v[136:139], v[132:135], v[164:167], 0
	v_mfma_f32_16x16x32_bf16 v[136:139], v[144:147], v[168:171], v[136:139]
	v_mfma_f32_16x16x32_bf16 v[120:123], v[156:159], v[164:167], 0
	v_mfma_f32_16x16x32_bf16 v[120:123], v[160:163], v[168:171], v[120:123]
	v_mfma_f32_16x16x32_bf16 v[112:115], v[116:119], v[172:175], 0
	v_mfma_f32_16x16x32_bf16 v[112:115], v[124:127], v[176:179], v[112:115]
	v_mfma_f32_16x16x32_bf16 v[104:107], v[148:151], v[172:175], 0
	v_mfma_f32_16x16x32_bf16 v[104:107], v[152:155], v[176:179], v[104:107]
	v_mfma_f32_16x16x32_bf16 v[108:111], v[132:135], v[172:175], 0
	v_mfma_f32_16x16x32_bf16 v[108:111], v[144:147], v[176:179], v[108:111]
	v_mfma_f32_16x16x32_bf16 v[100:103], v[156:159], v[172:175], 0
	v_mfma_f32_16x16x32_bf16 v[100:103], v[160:163], v[176:179], v[100:103]
	v_mfma_f32_16x16x32_bf16 v[96:99], v[116:119], v[180:183], 0
	v_mfma_f32_16x16x32_bf16 v[96:99], v[124:127], v[184:187], v[96:99]
	v_mfma_f32_16x16x32_bf16 v[88:91], v[148:151], v[180:183], 0
	v_mfma_f32_16x16x32_bf16 v[88:91], v[152:155], v[184:187], v[88:91]
	v_mfma_f32_16x16x32_bf16 v[92:95], v[132:135], v[180:183], 0
	v_mfma_f32_16x16x32_bf16 v[92:95], v[144:147], v[184:187], v[92:95]
	v_mfma_f32_16x16x32_bf16 v[84:87], v[156:159], v[180:183], 0
	v_mfma_f32_16x16x32_bf16 v[84:87], v[160:163], v[184:187], v[84:87]
	v_mfma_f32_16x16x32_bf16 v[80:83], v[116:119], v[196:199], 0
	v_mfma_f32_16x16x32_bf16 v[80:83], v[124:127], v[200:203], v[80:83]
	v_mfma_f32_16x16x32_bf16 v[72:75], v[148:151], v[196:199], 0
	v_mfma_f32_16x16x32_bf16 v[72:75], v[152:155], v[200:203], v[72:75]
	v_mfma_f32_16x16x32_bf16 v[76:79], v[132:135], v[196:199], 0
	v_mfma_f32_16x16x32_bf16 v[76:79], v[144:147], v[200:203], v[76:79]
	v_mfma_f32_16x16x32_bf16 v[68:71], v[156:159], v[196:199], 0
	v_mfma_f32_16x16x32_bf16 v[68:71], v[160:163], v[200:203], v[68:71]
	s_setprio 0
	s_barrier
	s_sleep 2
	s_add_i32 s49, s49, s30
	v_lshl_add_u64 v[204:205], s[24:25], 0, v[2:3]
	s_mov_b32 m0, s49
	ds_read_b128 v[164:167], v221 offset:16384
	ds_read_b128 v[168:171], v221 offset:17408
	ds_read_b128 v[172:175], v221 offset:18432
	ds_read_b128 v[176:179], v221 offset:19456
	ds_read_b128 v[180:183], v221 offset:20480
	ds_read_b128 v[184:187], v221 offset:21504
	ds_read_b128 v[196:199], v221 offset:22528
	ds_read_b128 v[200:203], v221 offset:23552
	global_load_lds_dwordx4 v[204:205], off
	s_add_i32 m0, s49, 0x2000
	s_add_u32 s50, s24, 0x80000
	v_lshl_add_u64 v[206:207], s[24:25], 0, v[190:191]
	s_addc_u32 s51, s25, 0
	s_add_i32 s49, s52, s30
	global_load_lds_dwordx4 v[206:207], off
	v_lshl_add_u64 v[208:209], s[50:51], 0, v[2:3]
	s_mov_b32 m0, s49
	v_lshl_add_u64 v[210:211], s[26:27], 0, v[188:189]
	global_load_lds_dwordx4 v[208:209], off
	v_lshl_add_u64 v[208:209], s[50:51], 0, v[190:191]
	s_add_i32 m0, s49, 0x2000
	s_nop 0
	global_load_lds_dwordx4 v[208:209], off
	v_lshl_add_u64 v[208:209], s[26:27], 0, v[0:1]
	s_mov_b32 m0, s21
	s_nop 0
	global_load_lds_dwordx4 v[208:209], off
	s_mov_b32 m0, s31
	s_nop 0
	global_load_lds_dwordx4 v[210:211], off
	s_waitcnt vmcnt(8)
	s_waitcnt lgkmcnt(0)
	s_barrier
	s_setprio 1
	s_waitcnt lgkmcnt(0)
	v_mfma_f32_16x16x32_bf16 v[64:67], v[116:119], v[164:167], 0
	v_mfma_f32_16x16x32_bf16 v[64:67], v[124:127], v[168:171], v[64:67]
	v_mfma_f32_16x16x32_bf16 v[56:59], v[148:151], v[164:167], 0
	v_mfma_f32_16x16x32_bf16 v[56:59], v[152:155], v[168:171], v[56:59]
	v_mfma_f32_16x16x32_bf16 v[60:63], v[132:135], v[164:167], 0
	v_mfma_f32_16x16x32_bf16 v[60:63], v[144:147], v[168:171], v[60:63]
	v_mfma_f32_16x16x32_bf16 v[52:55], v[156:159], v[164:167], 0
	v_mfma_f32_16x16x32_bf16 v[52:55], v[160:163], v[168:171], v[52:55]
	v_mfma_f32_16x16x32_bf16 v[48:51], v[116:119], v[172:175], 0
	v_mfma_f32_16x16x32_bf16 v[48:51], v[124:127], v[176:179], v[48:51]
	v_mfma_f32_16x16x32_bf16 v[40:43], v[148:151], v[172:175], 0
	v_mfma_f32_16x16x32_bf16 v[40:43], v[152:155], v[176:179], v[40:43]
	v_mfma_f32_16x16x32_bf16 v[44:47], v[132:135], v[172:175], 0
	v_mfma_f32_16x16x32_bf16 v[44:47], v[144:147], v[176:179], v[44:47]
	v_mfma_f32_16x16x32_bf16 v[36:39], v[156:159], v[172:175], 0
	v_mfma_f32_16x16x32_bf16 v[36:39], v[160:163], v[176:179], v[36:39]
	v_mfma_f32_16x16x32_bf16 v[32:35], v[116:119], v[180:183], 0
	v_mfma_f32_16x16x32_bf16 v[32:35], v[124:127], v[184:187], v[32:35]
	v_mfma_f32_16x16x32_bf16 v[24:27], v[148:151], v[180:183], 0
	v_mfma_f32_16x16x32_bf16 v[24:27], v[152:155], v[184:187], v[24:27]
	v_mfma_f32_16x16x32_bf16 v[28:31], v[132:135], v[180:183], 0
	v_mfma_f32_16x16x32_bf16 v[28:31], v[144:147], v[184:187], v[28:31]
	v_mfma_f32_16x16x32_bf16 v[20:23], v[156:159], v[180:183], 0
	v_mfma_f32_16x16x32_bf16 v[20:23], v[160:163], v[184:187], v[20:23]
	v_mfma_f32_16x16x32_bf16 v[16:19], v[116:119], v[196:199], 0
	v_mfma_f32_16x16x32_bf16 v[16:19], v[124:127], v[200:203], v[16:19]
	v_mfma_f32_16x16x32_bf16 v[8:11], v[148:151], v[196:199], 0
	v_mfma_f32_16x16x32_bf16 v[8:11], v[152:155], v[200:203], v[8:11]
	v_mfma_f32_16x16x32_bf16 v[12:15], v[132:135], v[196:199], 0
	v_mfma_f32_16x16x32_bf16 v[12:15], v[144:147], v[200:203], v[12:15]
	v_mfma_f32_16x16x32_bf16 v[4:7], v[156:159], v[196:199], 0
	v_mfma_f32_16x16x32_bf16 v[4:7], v[160:163], v[200:203], v[4:7]
	s_setprio 0
	s_barrier
	s_sleep 1
	s_add_i32 s49, 0, 0x18000
	s_add_i32 s50, 0, 0x1c000
	s_add_u32 s26, s26, 0x80000
	s_addc_u32 s27, s27, 0
	s_mov_b32 m0, s35
	v_lshl_add_u64 v[212:213], s[26:27], 0, v[0:1]
	global_load_lds_dwordx4 v[212:213], off
	v_lshl_add_u64 v[212:213], s[26:27], 0, v[188:189]
	s_mov_b32 m0, s40
	s_nop 0
	global_load_lds_dwordx4 v[212:213], off
	v_add_u32_e32 v144, s49, v219
	v_add_u32_e32 v160, s50, v219
	ds_read_b128 v[116:119], v144
	ds_read_b128 v[124:127], v144 offset:1024
	ds_read_b128 v[132:135], v144 offset:2048
	ds_read_b128 v[144:147], v144 offset:3072
	ds_read_b128 v[148:151], v160
	ds_read_b128 v[152:155], v160 offset:1024
	ds_read_b128 v[156:159], v160 offset:2048
	ds_read_b128 v[160:163], v160 offset:3072
	ds_read_b128 v[164:167], v221 offset:32768
	ds_read_b128 v[168:171], v221 offset:33792
	ds_read_b128 v[172:175], v221 offset:34816
	ds_read_b128 v[176:179], v221 offset:35840
	ds_read_b128 v[180:183], v221 offset:36864
	ds_read_b128 v[184:187], v221 offset:37888
	ds_read_b128 v[196:199], v221 offset:38912
	ds_read_b128 v[200:203], v221 offset:39936
	s_waitcnt vmcnt(8)
	s_waitcnt lgkmcnt(0)
	s_barrier
	s_setprio 1
	s_waitcnt lgkmcnt(0)
	v_mfma_f32_16x16x32_bf16 v[140:143], v[116:119], v[164:167], v[140:143]
	v_mfma_f32_16x16x32_bf16 v[140:143], v[124:127], v[168:171], v[140:143]
	v_mfma_f32_16x16x32_bf16 v[128:131], v[148:151], v[164:167], v[128:131]
	v_mfma_f32_16x16x32_bf16 v[128:131], v[152:155], v[168:171], v[128:131]
	v_mfma_f32_16x16x32_bf16 v[136:139], v[132:135], v[164:167], v[136:139]
	v_mfma_f32_16x16x32_bf16 v[136:139], v[144:147], v[168:171], v[136:139]
	v_mfma_f32_16x16x32_bf16 v[120:123], v[156:159], v[164:167], v[120:123]
	v_mfma_f32_16x16x32_bf16 v[120:123], v[160:163], v[168:171], v[120:123]
	v_mfma_f32_16x16x32_bf16 v[112:115], v[116:119], v[172:175], v[112:115]
	v_mfma_f32_16x16x32_bf16 v[112:115], v[124:127], v[176:179], v[112:115]
	v_mfma_f32_16x16x32_bf16 v[104:107], v[148:151], v[172:175], v[104:107]
	v_mfma_f32_16x16x32_bf16 v[104:107], v[152:155], v[176:179], v[104:107]
	v_mfma_f32_16x16x32_bf16 v[108:111], v[132:135], v[172:175], v[108:111]
	v_mfma_f32_16x16x32_bf16 v[108:111], v[144:147], v[176:179], v[108:111]
	v_mfma_f32_16x16x32_bf16 v[100:103], v[156:159], v[172:175], v[100:103]
	v_mfma_f32_16x16x32_bf16 v[100:103], v[160:163], v[176:179], v[100:103]
	v_mfma_f32_16x16x32_bf16 v[96:99], v[116:119], v[180:183], v[96:99]
	v_mfma_f32_16x16x32_bf16 v[96:99], v[124:127], v[184:187], v[96:99]
	v_mfma_f32_16x16x32_bf16 v[88:91], v[148:151], v[180:183], v[88:91]
	v_mfma_f32_16x16x32_bf16 v[88:91], v[152:155], v[184:187], v[88:91]
	v_mfma_f32_16x16x32_bf16 v[92:95], v[132:135], v[180:183], v[92:95]
	v_mfma_f32_16x16x32_bf16 v[92:95], v[144:147], v[184:187], v[92:95]
	v_mfma_f32_16x16x32_bf16 v[84:87], v[156:159], v[180:183], v[84:87]
	v_mfma_f32_16x16x32_bf16 v[84:87], v[160:163], v[184:187], v[84:87]
	v_mfma_f32_16x16x32_bf16 v[80:83], v[116:119], v[196:199], v[80:83]
	v_mfma_f32_16x16x32_bf16 v[80:83], v[124:127], v[200:203], v[80:83]
	v_mfma_f32_16x16x32_bf16 v[72:75], v[148:151], v[196:199], v[72:75]
	v_mfma_f32_16x16x32_bf16 v[72:75], v[152:155], v[200:203], v[72:75]
	v_mfma_f32_16x16x32_bf16 v[76:79], v[132:135], v[196:199], v[76:79]
	v_mfma_f32_16x16x32_bf16 v[76:79], v[144:147], v[200:203], v[76:79]
	v_mfma_f32_16x16x32_bf16 v[68:71], v[156:159], v[196:199], v[68:71]
	v_mfma_f32_16x16x32_bf16 v[68:71], v[160:163], v[200:203], v[68:71]
	s_setprio 0
	s_barrier
	s_sleep 2
	s_add_i32 s26, s49, s30
	v_lshl_add_u64 v[204:205], v[204:205], 0, s[66:67]
	s_mov_b32 m0, s26
	ds_read_b128 v[164:167], v221 offset:49152
	ds_read_b128 v[168:171], v221 offset:50176
	ds_read_b128 v[172:175], v221 offset:51200
	ds_read_b128 v[176:179], v221 offset:52224
	ds_read_b128 v[180:183], v221 offset:53248
	ds_read_b128 v[184:187], v221 offset:54272
	ds_read_b128 v[196:199], v221 offset:55296
	ds_read_b128 v[200:203], v221 offset:56320
	global_load_lds_dwordx4 v[204:205], off
	s_add_i32 m0, s26, 0x2000
	s_add_u32 s24, s24, 0x80080
	v_lshl_add_u64 v[204:205], v[206:207], 0, s[66:67]
	s_addc_u32 s25, s25, 0
	s_add_i32 s26, s50, s30
	global_load_lds_dwordx4 v[204:205], off
	v_lshl_add_u64 v[204:205], s[24:25], 0, v[2:3]
	s_mov_b32 m0, s26
	s_nop 0
	global_load_lds_dwordx4 v[204:205], off
	v_lshl_add_u64 v[204:205], s[24:25], 0, v[190:191]
	s_add_i32 m0, s26, 0x2000
	s_nop 0
	global_load_lds_dwordx4 v[204:205], off
	v_lshl_add_u64 v[204:205], v[208:209], 0, s[66:67]
	s_mov_b32 m0, s41
	s_nop 0
	global_load_lds_dwordx4 v[204:205], off
	v_lshl_add_u64 v[204:205], v[210:211], 0, s[66:67]
	s_mov_b32 m0, s42
	s_nop 0
	global_load_lds_dwordx4 v[204:205], off
	s_waitcnt vmcnt(8)
	s_waitcnt lgkmcnt(0)
	s_barrier
	s_setprio 1
	s_waitcnt lgkmcnt(0)
	v_mfma_f32_16x16x32_bf16 v[64:67], v[116:119], v[164:167], v[64:67]
	v_mfma_f32_16x16x32_bf16 v[64:67], v[124:127], v[168:171], v[64:67]
	v_mfma_f32_16x16x32_bf16 v[56:59], v[148:151], v[164:167], v[56:59]
	v_mfma_f32_16x16x32_bf16 v[56:59], v[152:155], v[168:171], v[56:59]
	v_mfma_f32_16x16x32_bf16 v[60:63], v[132:135], v[164:167], v[60:63]
	v_mfma_f32_16x16x32_bf16 v[60:63], v[144:147], v[168:171], v[60:63]
	v_mfma_f32_16x16x32_bf16 v[52:55], v[156:159], v[164:167], v[52:55]
	v_mfma_f32_16x16x32_bf16 v[52:55], v[160:163], v[168:171], v[52:55]
	v_mfma_f32_16x16x32_bf16 v[48:51], v[116:119], v[172:175], v[48:51]
	v_mfma_f32_16x16x32_bf16 v[48:51], v[124:127], v[176:179], v[48:51]
	v_mfma_f32_16x16x32_bf16 v[40:43], v[148:151], v[172:175], v[40:43]
	v_mfma_f32_16x16x32_bf16 v[40:43], v[152:155], v[176:179], v[40:43]
	v_mfma_f32_16x16x32_bf16 v[44:47], v[132:135], v[172:175], v[44:47]
	v_mfma_f32_16x16x32_bf16 v[44:47], v[144:147], v[176:179], v[44:47]
	v_mfma_f32_16x16x32_bf16 v[36:39], v[156:159], v[172:175], v[36:39]
	v_mfma_f32_16x16x32_bf16 v[36:39], v[160:163], v[176:179], v[36:39]
	v_mfma_f32_16x16x32_bf16 v[32:35], v[116:119], v[180:183], v[32:35]
	v_mfma_f32_16x16x32_bf16 v[32:35], v[124:127], v[184:187], v[32:35]
	v_mfma_f32_16x16x32_bf16 v[24:27], v[148:151], v[180:183], v[24:27]
	v_mfma_f32_16x16x32_bf16 v[24:27], v[152:155], v[184:187], v[24:27]
	v_mfma_f32_16x16x32_bf16 v[28:31], v[132:135], v[180:183], v[28:31]
	v_mfma_f32_16x16x32_bf16 v[28:31], v[144:147], v[184:187], v[28:31]
	v_mfma_f32_16x16x32_bf16 v[20:23], v[156:159], v[180:183], v[20:23]
	v_mfma_f32_16x16x32_bf16 v[20:23], v[160:163], v[184:187], v[20:23]
	v_mfma_f32_16x16x32_bf16 v[16:19], v[116:119], v[196:199], v[16:19]
	v_mfma_f32_16x16x32_bf16 v[16:19], v[124:127], v[200:203], v[16:19]
	v_mfma_f32_16x16x32_bf16 v[8:11], v[148:151], v[196:199], v[8:11]
	v_mfma_f32_16x16x32_bf16 v[8:11], v[152:155], v[200:203], v[8:11]
	v_mfma_f32_16x16x32_bf16 v[12:15], v[132:135], v[196:199], v[12:15]
	v_mfma_f32_16x16x32_bf16 v[12:15], v[144:147], v[200:203], v[12:15]
	v_mfma_f32_16x16x32_bf16 v[4:7], v[156:159], v[196:199], v[4:7]
	v_mfma_f32_16x16x32_bf16 v[4:7], v[160:163], v[200:203], v[4:7]
	s_setprio 0
	s_barrier
	s_add_i32 s48, s48, 2
	s_add_u32 s22, s22, 0x100
	s_addc_u32 s23, s23, 0
	s_add_u32 s46, s46, 0x100
	s_addc_u32 s47, s47, 0
	s_cmp_gt_u32 s48, 29
